# weight conversions in phase 1/4/7b/12 tails rewritten by hand (8 loads in flight, 2-item pipeline, v_cvt_pk_bf16_f32, nt cache hints) to stop them thrashing the caches under the GEMM tail units
# baseline (speedup 1.0000x reference)
.LBB0_87:
	s_abs_i32 s0, s30
	v_cvt_f32_u32_e32 v0, s0
	s_sub_i32 s1, 0, s0
	v_rcp_iflag_f32_e32 v0, v0
	s_nop 0
	v_mul_f32_e32 v0, 0x4f7ffffe, v0
	v_cvt_u32_f32_e32 v0, v0
	s_nop 0
	v_readfirstlane_b32 s3, v0
	s_mul_i32 s1, s1, s3
	s_mul_hi_u32 s1, s3, s1
	s_add_i32 s3, s3, s1
	s_mul_hi_u32 s1, s3, 0x580
	s_mul_i32 s1, s1, s0
	s_sub_i32 s1, 0x580, s1
	s_sub_i32 s3, s1, s0
	s_cmp_ge_u32 s1, s0
	s_cselect_b32 s1, s3, s1
	s_sub_i32 s3, s1, s0
	s_cmp_ge_u32 s1, s0
	s_cselect_b32 s3, s3, s1
	s_cmp_lg_u32 s3, 0
	s_cselect_b64 s[0:1], -1, 0
	s_cmp_ge_i32 s2, s3
	s_cselect_b64 s[4:5], -1, 0
	s_and_b64 s[4:5], s[0:1], s[4:5]
	s_xor_b64 s[6:7], s[0:1], s[4:5]
	s_and_b64 vcc, exec, s[6:7]
	s_cbranch_vccnz .LBB0_132
	s_sub_i32 s6, s30, s3
	s_sub_i32 s3, s2, s3
	s_lshl_b32 s3, s3, 3
	s_add_i32 s3, s57, s3
	s_and_b64 s[4:5], s[4:5], exec
	s_cselect_b32 s3, s3, s34
	s_lshl_b32 s4, s6, 3
	s_and_b64 s[0:1], s[0:1], exec
	s_cselect_b32 s10, s4, s80
	s_mul_i32 s11, s57, 0x2100
	v_lshrrev_b32_e32 v55, 3, v146
	v_and_b32_e32 v56, 7, v146
	v_mul_u32_u24_e32 v44, 0x84, v55
	v_lshl_add_u32 v44, v56, 4, v44
	v_add_u32_e32 v44, s11, v44
	v_add_u32_e32 v45, 0x420, v44
	v_add_u32_e32 v46, 0x840, v44
	v_add_u32_e32 v47, 0xc60, v44
	v_add_u32_e32 v48, 0x1080, v44
	v_add_u32_e32 v49, 0x14a0, v44
	v_add_u32_e32 v50, 0x18c0, v44
	v_add_u32_e32 v51, 0x1ce0, v44
	v_mul_u32_u24_e32 v52, 0x420, v56
	v_lshl_add_u32 v52, v55, 2, v52
	v_add_u32_e32 v52, s11, v52
	s_add_u32 s4, s52, 0x2d00000
	s_addc_u32 s5, s53, 0
	v_lshrrev_b32_e32 v55, 3, v146
	v_and_b32_e32 v56, 7, v146
	s_mov_b32 s11, 0x2000
	v_mul_lo_u32 v53, v55, s11
	v_lshl_add_u32 v53, v56, 4, v53
	s_mov_b32 s11, 0x2c00
	v_mul_lo_u32 v54, v55, s11
	v_lshl_add_u32 v54, v56, 4, v54
	s_mov_b32 s0, s3
	s_cmp_ge_u32 s0, 0x1600
	s_cbranch_scc1 .Lcv_done_p1dn
	s_lshr_b32 s18, s0, 6
	s_and_b32 s19, s0, 63
	s_lshl_b32 s15, s19, 5
	s_mul_i32 s16, s18, 0x80000
	s_lshl_b32 s15, s15, 2
	s_add_u32 s16, s16, s15
	s_add_u32 s6, s20, s16
	s_addc_u32 s7, s21, 0
	global_load_dwordx4 v[64:67], v53, s[6:7] nt
	s_add_u32 s6, s6, 0x10000
	s_addc_u32 s7, s7, 0
	global_load_dwordx4 v[68:71], v53, s[6:7] nt
	s_add_u32 s6, s6, 0x10000
	s_addc_u32 s7, s7, 0
	global_load_dwordx4 v[72:75], v53, s[6:7] nt
	s_add_u32 s6, s6, 0x10000
	s_addc_u32 s7, s7, 0
	global_load_dwordx4 v[76:79], v53, s[6:7] nt
	s_add_u32 s6, s6, 0x10000
	s_addc_u32 s7, s7, 0
	global_load_dwordx4 v[80:83], v53, s[6:7] nt
	s_add_u32 s6, s6, 0x10000
	s_addc_u32 s7, s7, 0
	global_load_dwordx4 v[84:87], v53, s[6:7] nt
	s_add_u32 s6, s6, 0x10000
	s_addc_u32 s7, s7, 0
	global_load_dwordx4 v[88:91], v53, s[6:7] nt
	s_add_u32 s6, s6, 0x10000
	s_addc_u32 s7, s7, 0
	global_load_dwordx4 v[92:95], v53, s[6:7] nt
	s_add_u32 s1, s0, s10
	s_cmp_ge_u32 s1, 0x1600
	s_cbranch_scc1 .Lcv_only1_p1dn
	s_lshr_b32 s18, s1, 6
	s_and_b32 s19, s1, 63
	s_lshl_b32 s15, s19, 5
	s_mul_i32 s16, s18, 0x80000
	s_lshl_b32 s15, s15, 2
	s_add_u32 s16, s16, s15
	s_add_u32 s6, s20, s16
	s_addc_u32 s7, s21, 0
	global_load_dwordx4 v[96:99], v53, s[6:7] nt
	s_add_u32 s6, s6, 0x10000
	s_addc_u32 s7, s7, 0
	global_load_dwordx4 v[100:103], v53, s[6:7] nt
	s_add_u32 s6, s6, 0x10000
	s_addc_u32 s7, s7, 0
	global_load_dwordx4 v[104:107], v53, s[6:7] nt
	s_add_u32 s6, s6, 0x10000
	s_addc_u32 s7, s7, 0
	global_load_dwordx4 v[108:111], v53, s[6:7] nt
	s_add_u32 s6, s6, 0x10000
	s_addc_u32 s7, s7, 0
	global_load_dwordx4 v[112:115], v53, s[6:7] nt
	s_add_u32 s6, s6, 0x10000
	s_addc_u32 s7, s7, 0
	global_load_dwordx4 v[116:119], v53, s[6:7] nt
	s_add_u32 s6, s6, 0x10000
	s_addc_u32 s7, s7, 0
	global_load_dwordx4 v[120:123], v53, s[6:7] nt
	s_add_u32 s6, s6, 0x10000
	s_addc_u32 s7, s7, 0
	global_load_dwordx4 v[124:127], v53, s[6:7] nt
	s_waitcnt vmcnt(8)
	s_branch .Lcv_procA_p1dn

.Lcv_procA_p1dn:
	s_lshr_b32 s18, s0, 6
	s_and_b32 s19, s0, 63
	ds_write2_b32 v44, v64, v65 offset1:1
	ds_write2_b32 v44, v66, v67 offset0:2 offset1:3
	ds_write2_b32 v45, v68, v69 offset1:1
	ds_write2_b32 v45, v70, v71 offset0:2 offset1:3
	ds_write2_b32 v46, v72, v73 offset1:1
	ds_write2_b32 v46, v74, v75 offset0:2 offset1:3
	ds_write2_b32 v47, v76, v77 offset1:1
	ds_write2_b32 v47, v78, v79 offset0:2 offset1:3
	ds_write2_b32 v48, v80, v81 offset1:1
	ds_write2_b32 v48, v82, v83 offset0:2 offset1:3
	ds_write2_b32 v49, v84, v85 offset1:1
	ds_write2_b32 v49, v86, v87 offset0:2 offset1:3
	ds_write2_b32 v50, v88, v89 offset1:1
	ds_write2_b32 v50, v90, v91 offset0:2 offset1:3
	ds_write2_b32 v51, v92, v93 offset1:1
	ds_write2_b32 v51, v94, v95 offset0:2 offset1:3
	s_mul_i32 s15, s19, 0x58000
	s_lshl_b32 s16, s18, 7
	s_add_u32 s15, s15, s16
	s_add_u32 s8, s4, s15
	s_addc_u32 s9, s5, 0
	s_waitcnt lgkmcnt(0)
	ds_read2_b32 v[8:9], v52 offset0:0 offset1:33
	ds_read2_b32 v[10:11], v52 offset0:66 offset1:99
	ds_read2_b32 v[12:13], v52 offset0:132 offset1:165
	ds_read2_b32 v[14:15], v52 offset0:198 offset1:231
	ds_read2_b32 v[16:17], v52 offset0:8 offset1:41
	ds_read2_b32 v[18:19], v52 offset0:74 offset1:107
	ds_read2_b32 v[20:21], v52 offset0:140 offset1:173
	ds_read2_b32 v[22:23], v52 offset0:206 offset1:239
	ds_read2_b32 v[24:25], v52 offset0:16 offset1:49
	ds_read2_b32 v[26:27], v52 offset0:82 offset1:115
	ds_read2_b32 v[28:29], v52 offset0:148 offset1:181
	ds_read2_b32 v[30:31], v52 offset0:214 offset1:247
	ds_read2_b32 v[32:33], v52 offset0:24 offset1:57
	ds_read2_b32 v[34:35], v52 offset0:90 offset1:123
	ds_read2_b32 v[36:37], v52 offset0:156 offset1:189
	ds_read2_b32 v[38:39], v52 offset0:222 offset1:255
	s_waitcnt lgkmcnt(12)
	v_cvt_pk_bf16_f32 v128, v8, v9
	v_cvt_pk_bf16_f32 v129, v10, v11
	v_cvt_pk_bf16_f32 v130, v12, v13
	v_cvt_pk_bf16_f32 v131, v14, v15
	global_store_dwordx4 v54, v[128:131], s[8:9] nt
	s_add_u32 s8, s8, 0x16000
	s_addc_u32 s9, s9, 0
	s_waitcnt lgkmcnt(8)
	v_cvt_pk_bf16_f32 v132, v16, v17
	v_cvt_pk_bf16_f32 v133, v18, v19
	v_cvt_pk_bf16_f32 v134, v20, v21
	v_cvt_pk_bf16_f32 v135, v22, v23
	global_store_dwordx4 v54, v[132:135], s[8:9] nt
	s_add_u32 s8, s8, 0x16000
	s_addc_u32 s9, s9, 0
	s_waitcnt lgkmcnt(4)
	v_cvt_pk_bf16_f32 v136, v24, v25
	v_cvt_pk_bf16_f32 v137, v26, v27
	v_cvt_pk_bf16_f32 v138, v28, v29
	v_cvt_pk_bf16_f32 v139, v30, v31
	global_store_dwordx4 v54, v[136:139], s[8:9] nt
	s_add_u32 s8, s8, 0x16000
	s_addc_u32 s9, s9, 0
	s_waitcnt lgkmcnt(0)
	v_cvt_pk_bf16_f32 v140, v32, v33
	v_cvt_pk_bf16_f32 v141, v34, v35
	v_cvt_pk_bf16_f32 v142, v36, v37
	v_cvt_pk_bf16_f32 v143, v38, v39
	global_store_dwordx4 v54, v[140:143], s[8:9] nt
	s_cmp_ge_u32 s1, 0x1600
	s_cbranch_scc1 .Lcv_done_p1dn
	s_add_u32 s0, s1, s10
	s_cmp_ge_u32 s0, 0x1600
	s_cbranch_scc1 .Lcv_tailB_p1dn
	s_lshr_b32 s18, s0, 6
	s_and_b32 s19, s0, 63
	s_lshl_b32 s15, s19, 5
	s_mul_i32 s16, s18, 0x80000
	s_lshl_b32 s15, s15, 2
	s_add_u32 s16, s16, s15
	s_add_u32 s6, s20, s16
	s_addc_u32 s7, s21, 0
	global_load_dwordx4 v[64:67], v53, s[6:7] nt
	s_add_u32 s6, s6, 0x10000
	s_addc_u32 s7, s7, 0
	global_load_dwordx4 v[68:71], v53, s[6:7] nt
	s_add_u32 s6, s6, 0x10000
	s_addc_u32 s7, s7, 0
	global_load_dwordx4 v[72:75], v53, s[6:7] nt
	s_add_u32 s6, s6, 0x10000
	s_addc_u32 s7, s7, 0
	global_load_dwordx4 v[76:79], v53, s[6:7] nt
	s_add_u32 s6, s6, 0x10000
	s_addc_u32 s7, s7, 0
	global_load_dwordx4 v[80:83], v53, s[6:7] nt
	s_add_u32 s6, s6, 0x10000
	s_addc_u32 s7, s7, 0
	global_load_dwordx4 v[84:87], v53, s[6:7] nt
	s_add_u32 s6, s6, 0x10000
	s_addc_u32 s7, s7, 0
	global_load_dwordx4 v[88:91], v53, s[6:7] nt
	s_add_u32 s6, s6, 0x10000
	s_addc_u32 s7, s7, 0
	global_load_dwordx4 v[92:95], v53, s[6:7] nt
	s_waitcnt vmcnt(12)
	s_branch .Lcv_procB_p1dn

.Lcv_procB_p1dn:
	s_lshr_b32 s18, s1, 6
	s_and_b32 s19, s1, 63
	ds_write2_b32 v44, v96, v97 offset1:1
	ds_write2_b32 v44, v98, v99 offset0:2 offset1:3
	ds_write2_b32 v45, v100, v101 offset1:1
	ds_write2_b32 v45, v102, v103 offset0:2 offset1:3
	ds_write2_b32 v46, v104, v105 offset1:1
	ds_write2_b32 v46, v106, v107 offset0:2 offset1:3
	ds_write2_b32 v47, v108, v109 offset1:1
	ds_write2_b32 v47, v110, v111 offset0:2 offset1:3
	ds_write2_b32 v48, v112, v113 offset1:1
	ds_write2_b32 v48, v114, v115 offset0:2 offset1:3
	ds_write2_b32 v49, v116, v117 offset1:1
	ds_write2_b32 v49, v118, v119 offset0:2 offset1:3
	ds_write2_b32 v50, v120, v121 offset1:1
	ds_write2_b32 v50, v122, v123 offset0:2 offset1:3
	ds_write2_b32 v51, v124, v125 offset1:1
	ds_write2_b32 v51, v126, v127 offset0:2 offset1:3
	s_mul_i32 s15, s19, 0x58000
	s_lshl_b32 s16, s18, 7
	s_add_u32 s15, s15, s16
	s_add_u32 s8, s4, s15
	s_addc_u32 s9, s5, 0
	s_waitcnt lgkmcnt(0)
	ds_read2_b32 v[8:9], v52 offset0:0 offset1:33
	ds_read2_b32 v[10:11], v52 offset0:66 offset1:99
	ds_read2_b32 v[12:13], v52 offset0:132 offset1:165
	ds_read2_b32 v[14:15], v52 offset0:198 offset1:231
	ds_read2_b32 v[16:17], v52 offset0:8 offset1:41
	ds_read2_b32 v[18:19], v52 offset0:74 offset1:107
	ds_read2_b32 v[20:21], v52 offset0:140 offset1:173
	ds_read2_b32 v[22:23], v52 offset0:206 offset1:239
	ds_read2_b32 v[24:25], v52 offset0:16 offset1:49
	ds_read2_b32 v[26:27], v52 offset0:82 offset1:115
	ds_read2_b32 v[28:29], v52 offset0:148 offset1:181
	ds_read2_b32 v[30:31], v52 offset0:214 offset1:247
	ds_read2_b32 v[32:33], v52 offset0:24 offset1:57
	ds_read2_b32 v[34:35], v52 offset0:90 offset1:123
	ds_read2_b32 v[36:37], v52 offset0:156 offset1:189
	ds_read2_b32 v[38:39], v52 offset0:222 offset1:255
	s_waitcnt lgkmcnt(12)
	v_cvt_pk_bf16_f32 v128, v8, v9
	v_cvt_pk_bf16_f32 v129, v10, v11
	v_cvt_pk_bf16_f32 v130, v12, v13
	v_cvt_pk_bf16_f32 v131, v14, v15
	global_store_dwordx4 v54, v[128:131], s[8:9] nt
	s_add_u32 s8, s8, 0x16000
	s_addc_u32 s9, s9, 0
	s_waitcnt lgkmcnt(8)
	v_cvt_pk_bf16_f32 v132, v16, v17
	v_cvt_pk_bf16_f32 v133, v18, v19
	v_cvt_pk_bf16_f32 v134, v20, v21
	v_cvt_pk_bf16_f32 v135, v22, v23
	global_store_dwordx4 v54, v[132:135], s[8:9] nt
	s_add_u32 s8, s8, 0x16000
	s_addc_u32 s9, s9, 0
	s_waitcnt lgkmcnt(4)
	v_cvt_pk_bf16_f32 v136, v24, v25
	v_cvt_pk_bf16_f32 v137, v26, v27
	v_cvt_pk_bf16_f32 v138, v28, v29
	v_cvt_pk_bf16_f32 v139, v30, v31
	global_store_dwordx4 v54, v[136:139], s[8:9] nt
	s_add_u32 s8, s8, 0x16000
	s_addc_u32 s9, s9, 0
	s_waitcnt lgkmcnt(0)
	v_cvt_pk_bf16_f32 v140, v32, v33
	v_cvt_pk_bf16_f32 v141, v34, v35
	v_cvt_pk_bf16_f32 v142, v36, v37
	v_cvt_pk_bf16_f32 v143, v38, v39
	global_store_dwordx4 v54, v[140:143], s[8:9] nt
	s_cmp_ge_u32 s0, 0x1600
	s_cbranch_scc1 .Lcv_done_p1dn
	s_add_u32 s1, s0, s10
	s_cmp_ge_u32 s1, 0x1600
	s_cbranch_scc1 .Lcv_tailA_p1dn
	s_lshr_b32 s18, s1, 6
	s_and_b32 s19, s1, 63
	s_lshl_b32 s15, s19, 5
	s_mul_i32 s16, s18, 0x80000
	s_lshl_b32 s15, s15, 2
	s_add_u32 s16, s16, s15
	s_add_u32 s6, s20, s16
	s_addc_u32 s7, s21, 0
	global_load_dwordx4 v[96:99], v53, s[6:7] nt
	s_add_u32 s6, s6, 0x10000
	s_addc_u32 s7, s7, 0
	global_load_dwordx4 v[100:103], v53, s[6:7] nt
	s_add_u32 s6, s6, 0x10000
	s_addc_u32 s7, s7, 0
	global_load_dwordx4 v[104:107], v53, s[6:7] nt
	s_add_u32 s6, s6, 0x10000
	s_addc_u32 s7, s7, 0
	global_load_dwordx4 v[108:111], v53, s[6:7] nt
	s_add_u32 s6, s6, 0x10000
	s_addc_u32 s7, s7, 0
	global_load_dwordx4 v[112:115], v53, s[6:7] nt
	s_add_u32 s6, s6, 0x10000
	s_addc_u32 s7, s7, 0
	global_load_dwordx4 v[116:119], v53, s[6:7] nt
	s_add_u32 s6, s6, 0x10000
	s_addc_u32 s7, s7, 0
	global_load_dwordx4 v[120:123], v53, s[6:7] nt
	s_add_u32 s6, s6, 0x10000
	s_addc_u32 s7, s7, 0
	global_load_dwordx4 v[124:127], v53, s[6:7] nt
	s_waitcnt vmcnt(12)
	s_branch .Lcv_procA_p1dn

.Lcv_done_p1dn:
	s_add_u32 s4, s52, 0x4300000
	s_addc_u32 s5, s53, 0
	v_lshrrev_b32_e32 v55, 3, v146
	v_and_b32_e32 v56, 7, v146
	s_mov_b32 s11, 0xa740
	v_mul_lo_u32 v53, v55, s11
	v_lshl_add_u32 v53, v56, 4, v53
	s_mov_b32 s11, 0x1000
	v_mul_lo_u32 v54, v55, s11
	v_lshl_add_u32 v54, v56, 4, v54
	s_mov_b32 s0, s3
	s_cmp_ge_u32 s0, 0x2a00
	s_cbranch_scc1 .Lcv_done_p1win
	s_mul_hi_u32 s18, s0, 0xc30c31
	s_mul_i32 s19, s18, 336
	s_sub_u32 s19, s0, s19
	s_mov_b32 s16, 0
	s_cmp_ge_u32 s19, 96
	s_cselect_b32 s16, 16, s16
	s_cmp_ge_u32 s19, 192
	s_cselect_b32 s16, 464, s16
	s_cmp_ge_u32 s19, 320
	s_cselect_b32 s16, -7168, s16
	s_cmp_ge_u32 s19, 321
	s_cselect_b32 s16, -4112, s16
	s_cmp_ge_u32 s19, 328
	s_cselect_b32 s16, -4144, s16
	s_lshl_b32 s15, s19, 5
	s_add_i32 s15, s15, s16
	s_mul_i32 s16, s18, 0x29d000
	s_lshl_b32 s15, s15, 2
	s_add_u32 s16, s16, s15
	s_add_u32 s6, s24, s16
	s_addc_u32 s7, s25, 0
	global_load_dwordx4 v[64:67], v53, s[6:7] nt
	s_add_u32 s6, s6, 0x53a00
	s_addc_u32 s7, s7, 0
	global_load_dwordx4 v[68:71], v53, s[6:7] nt
	s_add_u32 s6, s6, 0x53a00
	s_addc_u32 s7, s7, 0
	global_load_dwordx4 v[72:75], v53, s[6:7] nt
	s_add_u32 s6, s6, 0x53a00
	s_addc_u32 s7, s7, 0
	global_load_dwordx4 v[76:79], v53, s[6:7] nt
	s_add_u32 s6, s6, 0x53a00
	s_addc_u32 s7, s7, 0
	global_load_dwordx4 v[80:83], v53, s[6:7] nt
	s_add_u32 s6, s6, 0x53a00
	s_addc_u32 s7, s7, 0
	global_load_dwordx4 v[84:87], v53, s[6:7] nt
	s_add_u32 s6, s6, 0x53a00
	s_addc_u32 s7, s7, 0
	global_load_dwordx4 v[88:91], v53, s[6:7] nt
	s_add_u32 s6, s6, 0x53a00
	s_addc_u32 s7, s7, 0
	global_load_dwordx4 v[92:95], v53, s[6:7] nt
	s_add_u32 s1, s0, s10
	s_cmp_ge_u32 s1, 0x2a00
	s_cbranch_scc1 .Lcv_only1_p1win
	s_mul_hi_u32 s18, s1, 0xc30c31
	s_mul_i32 s19, s18, 336
	s_sub_u32 s19, s1, s19
	s_mov_b32 s16, 0
	s_cmp_ge_u32 s19, 96
	s_cselect_b32 s16, 16, s16
	s_cmp_ge_u32 s19, 192
	s_cselect_b32 s16, 464, s16
	s_cmp_ge_u32 s19, 320
	s_cselect_b32 s16, -7168, s16
	s_cmp_ge_u32 s19, 321
	s_cselect_b32 s16, -4112, s16
	s_cmp_ge_u32 s19, 328
	s_cselect_b32 s16, -4144, s16
	s_lshl_b32 s15, s19, 5
	s_add_i32 s15, s15, s16
	s_mul_i32 s16, s18, 0x29d000
	s_lshl_b32 s15, s15, 2
	s_add_u32 s16, s16, s15
	s_add_u32 s6, s24, s16
	s_addc_u32 s7, s25, 0
	global_load_dwordx4 v[96:99], v53, s[6:7] nt
	s_add_u32 s6, s6, 0x53a00
	s_addc_u32 s7, s7, 0
	global_load_dwordx4 v[100:103], v53, s[6:7] nt
	s_add_u32 s6, s6, 0x53a00
	s_addc_u32 s7, s7, 0
	global_load_dwordx4 v[104:107], v53, s[6:7] nt
	s_add_u32 s6, s6, 0x53a00
	s_addc_u32 s7, s7, 0
	global_load_dwordx4 v[108:111], v53, s[6:7] nt
	s_add_u32 s6, s6, 0x53a00
	s_addc_u32 s7, s7, 0
	global_load_dwordx4 v[112:115], v53, s[6:7] nt
	s_add_u32 s6, s6, 0x53a00
	s_addc_u32 s7, s7, 0
	global_load_dwordx4 v[116:119], v53, s[6:7] nt
	s_add_u32 s6, s6, 0x53a00
	s_addc_u32 s7, s7, 0
	global_load_dwordx4 v[120:123], v53, s[6:7] nt
	s_add_u32 s6, s6, 0x53a00
	s_addc_u32 s7, s7, 0
	global_load_dwordx4 v[124:127], v53, s[6:7] nt
	s_waitcnt vmcnt(8)
	s_branch .Lcv_procA_p1win

.Lcv_nz_p1win_A:
	ds_write2_b32 v44, v64, v65 offset1:1
	ds_write2_b32 v44, v66, v67 offset0:2 offset1:3
	ds_write2_b32 v45, v68, v69 offset1:1
	ds_write2_b32 v45, v70, v71 offset0:2 offset1:3
	ds_write2_b32 v46, v72, v73 offset1:1
	ds_write2_b32 v46, v74, v75 offset0:2 offset1:3
	ds_write2_b32 v47, v76, v77 offset1:1
	ds_write2_b32 v47, v78, v79 offset0:2 offset1:3
	ds_write2_b32 v48, v80, v81 offset1:1
	ds_write2_b32 v48, v82, v83 offset0:2 offset1:3
	ds_write2_b32 v49, v84, v85 offset1:1
	ds_write2_b32 v49, v86, v87 offset0:2 offset1:3
	ds_write2_b32 v50, v88, v89 offset1:1
	ds_write2_b32 v50, v90, v91 offset0:2 offset1:3
	ds_write2_b32 v51, v92, v93 offset1:1
	ds_write2_b32 v51, v94, v95 offset0:2 offset1:3
	s_mul_i32 s15, s19, 0x20000
	s_lshl_b32 s16, s18, 7
	s_add_u32 s15, s15, s16
	s_add_u32 s8, s4, s15
	s_addc_u32 s9, s5, 0
	s_waitcnt lgkmcnt(0)
	ds_read2_b32 v[8:9], v52 offset0:0 offset1:33
	ds_read2_b32 v[10:11], v52 offset0:66 offset1:99
	ds_read2_b32 v[12:13], v52 offset0:132 offset1:165
	ds_read2_b32 v[14:15], v52 offset0:198 offset1:231
	ds_read2_b32 v[16:17], v52 offset0:8 offset1:41
	ds_read2_b32 v[18:19], v52 offset0:74 offset1:107
	ds_read2_b32 v[20:21], v52 offset0:140 offset1:173
	ds_read2_b32 v[22:23], v52 offset0:206 offset1:239
	ds_read2_b32 v[24:25], v52 offset0:16 offset1:49
	ds_read2_b32 v[26:27], v52 offset0:82 offset1:115
	ds_read2_b32 v[28:29], v52 offset0:148 offset1:181
	ds_read2_b32 v[30:31], v52 offset0:214 offset1:247
	ds_read2_b32 v[32:33], v52 offset0:24 offset1:57
	ds_read2_b32 v[34:35], v52 offset0:90 offset1:123
	ds_read2_b32 v[36:37], v52 offset0:156 offset1:189
	ds_read2_b32 v[38:39], v52 offset0:222 offset1:255
	s_waitcnt lgkmcnt(12)
	v_cvt_pk_bf16_f32 v128, v8, v9
	v_cvt_pk_bf16_f32 v129, v10, v11
	v_cvt_pk_bf16_f32 v130, v12, v13
	v_cvt_pk_bf16_f32 v131, v14, v15
	global_store_dwordx4 v54, v[128:131], s[8:9] nt
	s_add_u32 s8, s8, 0x8000
	s_addc_u32 s9, s9, 0
	s_waitcnt lgkmcnt(8)
	v_cvt_pk_bf16_f32 v132, v16, v17
	v_cvt_pk_bf16_f32 v133, v18, v19
	v_cvt_pk_bf16_f32 v134, v20, v21
	v_cvt_pk_bf16_f32 v135, v22, v23
	global_store_dwordx4 v54, v[132:135], s[8:9] nt
	s_add_u32 s8, s8, 0x8000
	s_addc_u32 s9, s9, 0
	s_waitcnt lgkmcnt(4)
	v_cvt_pk_bf16_f32 v136, v24, v25
	v_cvt_pk_bf16_f32 v137, v26, v27
	v_cvt_pk_bf16_f32 v138, v28, v29
	v_cvt_pk_bf16_f32 v139, v30, v31
	global_store_dwordx4 v54, v[136:139], s[8:9] nt
	s_add_u32 s8, s8, 0x8000
	s_addc_u32 s9, s9, 0
	s_waitcnt lgkmcnt(0)
	v_cvt_pk_bf16_f32 v140, v32, v33
	v_cvt_pk_bf16_f32 v141, v34, v35
	v_cvt_pk_bf16_f32 v142, v36, v37
	v_cvt_pk_bf16_f32 v143, v38, v39
	global_store_dwordx4 v54, v[140:143], s[8:9] nt
	s_cmp_ge_u32 s1, 0x2a00
	s_cbranch_scc1 .Lcv_done_p1win
	s_add_u32 s0, s1, s10
	s_cmp_ge_u32 s0, 0x2a00
	s_cbranch_scc1 .Lcv_tailB_p1win
	s_mul_hi_u32 s18, s0, 0xc30c31
	s_mul_i32 s19, s18, 336
	s_sub_u32 s19, s0, s19
	s_mov_b32 s16, 0
	s_cmp_ge_u32 s19, 96
	s_cselect_b32 s16, 16, s16
	s_cmp_ge_u32 s19, 192
	s_cselect_b32 s16, 464, s16
	s_cmp_ge_u32 s19, 320
	s_cselect_b32 s16, -7168, s16
	s_cmp_ge_u32 s19, 321
	s_cselect_b32 s16, -4112, s16
	s_cmp_ge_u32 s19, 328
	s_cselect_b32 s16, -4144, s16
	s_lshl_b32 s15, s19, 5
	s_add_i32 s15, s15, s16
	s_mul_i32 s16, s18, 0x29d000
	s_lshl_b32 s15, s15, 2
	s_add_u32 s16, s16, s15
	s_add_u32 s6, s24, s16
	s_addc_u32 s7, s25, 0
	global_load_dwordx4 v[64:67], v53, s[6:7] nt
	s_add_u32 s6, s6, 0x53a00
	s_addc_u32 s7, s7, 0
	global_load_dwordx4 v[68:71], v53, s[6:7] nt
	s_add_u32 s6, s6, 0x53a00
	s_addc_u32 s7, s7, 0
	global_load_dwordx4 v[72:75], v53, s[6:7] nt
	s_add_u32 s6, s6, 0x53a00
	s_addc_u32 s7, s7, 0
	global_load_dwordx4 v[76:79], v53, s[6:7] nt
	s_add_u32 s6, s6, 0x53a00
	s_addc_u32 s7, s7, 0
	global_load_dwordx4 v[80:83], v53, s[6:7] nt
	s_add_u32 s6, s6, 0x53a00
	s_addc_u32 s7, s7, 0
	global_load_dwordx4 v[84:87], v53, s[6:7] nt
	s_add_u32 s6, s6, 0x53a00
	s_addc_u32 s7, s7, 0
	global_load_dwordx4 v[88:91], v53, s[6:7] nt
	s_add_u32 s6, s6, 0x53a00
	s_addc_u32 s7, s7, 0
	global_load_dwordx4 v[92:95], v53, s[6:7] nt
	s_waitcnt vmcnt(12)
	s_branch .Lcv_procB_p1win

.Lcv_nz_p1win_B:
	ds_write2_b32 v44, v96, v97 offset1:1
	ds_write2_b32 v44, v98, v99 offset0:2 offset1:3
	ds_write2_b32 v45, v100, v101 offset1:1
	ds_write2_b32 v45, v102, v103 offset0:2 offset1:3
	ds_write2_b32 v46, v104, v105 offset1:1
	ds_write2_b32 v46, v106, v107 offset0:2 offset1:3
	ds_write2_b32 v47, v108, v109 offset1:1
	ds_write2_b32 v47, v110, v111 offset0:2 offset1:3
	ds_write2_b32 v48, v112, v113 offset1:1
	ds_write2_b32 v48, v114, v115 offset0:2 offset1:3
	ds_write2_b32 v49, v116, v117 offset1:1
	ds_write2_b32 v49, v118, v119 offset0:2 offset1:3
	ds_write2_b32 v50, v120, v121 offset1:1
	ds_write2_b32 v50, v122, v123 offset0:2 offset1:3
	ds_write2_b32 v51, v124, v125 offset1:1
	ds_write2_b32 v51, v126, v127 offset0:2 offset1:3
	s_mul_i32 s15, s19, 0x20000
	s_lshl_b32 s16, s18, 7
	s_add_u32 s15, s15, s16
	s_add_u32 s8, s4, s15
	s_addc_u32 s9, s5, 0
	s_waitcnt lgkmcnt(0)
	ds_read2_b32 v[8:9], v52 offset0:0 offset1:33
	ds_read2_b32 v[10:11], v52 offset0:66 offset1:99
	ds_read2_b32 v[12:13], v52 offset0:132 offset1:165
	ds_read2_b32 v[14:15], v52 offset0:198 offset1:231
	ds_read2_b32 v[16:17], v52 offset0:8 offset1:41
	ds_read2_b32 v[18:19], v52 offset0:74 offset1:107
	ds_read2_b32 v[20:21], v52 offset0:140 offset1:173
	ds_read2_b32 v[22:23], v52 offset0:206 offset1:239
	ds_read2_b32 v[24:25], v52 offset0:16 offset1:49
	ds_read2_b32 v[26:27], v52 offset0:82 offset1:115
	ds_read2_b32 v[28:29], v52 offset0:148 offset1:181
	ds_read2_b32 v[30:31], v52 offset0:214 offset1:247
	ds_read2_b32 v[32:33], v52 offset0:24 offset1:57
	ds_read2_b32 v[34:35], v52 offset0:90 offset1:123
	ds_read2_b32 v[36:37], v52 offset0:156 offset1:189
	ds_read2_b32 v[38:39], v52 offset0:222 offset1:255
	s_waitcnt lgkmcnt(12)
	v_cvt_pk_bf16_f32 v128, v8, v9
	v_cvt_pk_bf16_f32 v129, v10, v11
	v_cvt_pk_bf16_f32 v130, v12, v13
	v_cvt_pk_bf16_f32 v131, v14, v15
	global_store_dwordx4 v54, v[128:131], s[8:9] nt
	s_add_u32 s8, s8, 0x8000
	s_addc_u32 s9, s9, 0
	s_waitcnt lgkmcnt(8)
	v_cvt_pk_bf16_f32 v132, v16, v17
	v_cvt_pk_bf16_f32 v133, v18, v19
	v_cvt_pk_bf16_f32 v134, v20, v21
	v_cvt_pk_bf16_f32 v135, v22, v23
	global_store_dwordx4 v54, v[132:135], s[8:9] nt
	s_add_u32 s8, s8, 0x8000
	s_addc_u32 s9, s9, 0
	s_waitcnt lgkmcnt(4)
	v_cvt_pk_bf16_f32 v136, v24, v25
	v_cvt_pk_bf16_f32 v137, v26, v27
	v_cvt_pk_bf16_f32 v138, v28, v29
	v_cvt_pk_bf16_f32 v139, v30, v31
	global_store_dwordx4 v54, v[136:139], s[8:9] nt
	s_add_u32 s8, s8, 0x8000
	s_addc_u32 s9, s9, 0
	s_waitcnt lgkmcnt(0)
	v_cvt_pk_bf16_f32 v140, v32, v33
	v_cvt_pk_bf16_f32 v141, v34, v35
	v_cvt_pk_bf16_f32 v142, v36, v37
	v_cvt_pk_bf16_f32 v143, v38, v39
	global_store_dwordx4 v54, v[140:143], s[8:9] nt
	s_cmp_ge_u32 s0, 0x2a00
	s_cbranch_scc1 .Lcv_done_p1win
	s_add_u32 s1, s0, s10
	s_cmp_ge_u32 s1, 0x2a00
	s_cbranch_scc1 .Lcv_tailA_p1win
	s_mul_hi_u32 s18, s1, 0xc30c31
	s_mul_i32 s19, s18, 336
	s_sub_u32 s19, s1, s19
	s_mov_b32 s16, 0
	s_cmp_ge_u32 s19, 96
	s_cselect_b32 s16, 16, s16
	s_cmp_ge_u32 s19, 192
	s_cselect_b32 s16, 464, s16
	s_cmp_ge_u32 s19, 320
	s_cselect_b32 s16, -7168, s16
	s_cmp_ge_u32 s19, 321
	s_cselect_b32 s16, -4112, s16
	s_cmp_ge_u32 s19, 328
	s_cselect_b32 s16, -4144, s16
	s_lshl_b32 s15, s19, 5
	s_add_i32 s15, s15, s16
	s_mul_i32 s16, s18, 0x29d000
	s_lshl_b32 s15, s15, 2
	s_add_u32 s16, s16, s15
	s_add_u32 s6, s24, s16
	s_addc_u32 s7, s25, 0
	global_load_dwordx4 v[96:99], v53, s[6:7] nt
	s_add_u32 s6, s6, 0x53a00
	s_addc_u32 s7, s7, 0
	global_load_dwordx4 v[100:103], v53, s[6:7] nt
	s_add_u32 s6, s6, 0x53a00
	s_addc_u32 s7, s7, 0
	global_load_dwordx4 v[104:107], v53, s[6:7] nt
	s_add_u32 s6, s6, 0x53a00
	s_addc_u32 s7, s7, 0
	global_load_dwordx4 v[108:111], v53, s[6:7] nt
	s_add_u32 s6, s6, 0x53a00
	s_addc_u32 s7, s7, 0
	global_load_dwordx4 v[112:115], v53, s[6:7] nt
	s_add_u32 s6, s6, 0x53a00
	s_addc_u32 s7, s7, 0
	global_load_dwordx4 v[116:119], v53, s[6:7] nt
	s_add_u32 s6, s6, 0x53a00
	s_addc_u32 s7, s7, 0
	global_load_dwordx4 v[120:123], v53, s[6:7] nt
	s_add_u32 s6, s6, 0x53a00
	s_addc_u32 s7, s7, 0
	global_load_dwordx4 v[124:127], v53, s[6:7] nt
	s_waitcnt vmcnt(12)
	s_branch .Lcv_procA_p1win

.LBB0_398:
	s_abs_i32 s0, s30
	v_cvt_f32_u32_e32 v0, s0
	s_sub_i32 s1, 0, s0
	v_rcp_iflag_f32_e32 v0, v0
	s_nop 0
	v_mul_f32_e32 v0, 0x4f7ffffe, v0
	v_cvt_u32_f32_e32 v0, v0
	s_nop 0
	v_readfirstlane_b32 s3, v0
	s_mul_i32 s1, s1, s3
	s_mul_hi_u32 s1, s3, s1
	s_add_i32 s3, s3, s1
	s_mul_hi_u32 s1, s3, 0x540
	s_mul_i32 s1, s1, s0
	s_sub_i32 s1, 0x540, s1
	s_sub_i32 s3, s1, s0
	s_cmp_ge_u32 s1, s0
	s_cselect_b32 s1, s3, s1
	s_sub_i32 s3, s1, s0
	s_cmp_ge_u32 s1, s0
	s_cselect_b32 s3, s3, s1
	s_cmp_lg_u32 s3, 0
	s_cselect_b64 s[0:1], -1, 0
	s_cmp_ge_i32 s2, s3
	s_cselect_b64 s[4:5], -1, 0
	s_and_b64 s[4:5], s[0:1], s[4:5]
	s_xor_b64 s[6:7], s[0:1], s[4:5]
	s_and_b64 vcc, exec, s[6:7]
	s_cbranch_vccnz .LBB0_423
	s_sub_i32 s6, s30, s3
	s_sub_i32 s3, s2, s3
	s_lshl_b32 s3, s3, 3
	s_add_i32 s3, s57, s3
	s_and_b64 s[4:5], s[4:5], exec
	s_cselect_b32 s3, s3, s34
	s_lshl_b32 s4, s6, 3
	s_and_b64 s[0:1], s[0:1], exec
	s_cselect_b32 s8, s4, s80
	v_readlane_b32 s60, v240, 19
	v_readlane_b32 s61, v240, 20
	v_readlane_b32 s62, v240, 21
	v_readlane_b32 s63, v240, 22
	v_readlane_b32 s64, v240, 23
	v_readlane_b32 s65, v240, 24
	v_readlane_b32 s66, v240, 25
	v_readlane_b32 s67, v240, 26
	v_readlane_b32 s68, v240, 27
	v_readlane_b32 s69, v240, 28
	v_readlane_b32 s70, v240, 29
	v_readlane_b32 s71, v240, 30
	v_readlane_b32 s72, v240, 31
	v_readlane_b32 s73, v240, 32
	v_readlane_b32 s74, v240, 33
	v_readlane_b32 s75, v240, 34
	s_mul_i32 s4, s57, 0x2100
	v_lshrrev_b32_e32 v55, 3, v146
	v_and_b32_e32 v56, 7, v146
	v_mul_u32_u24_e32 v44, 0x84, v55
	v_lshl_add_u32 v44, v56, 4, v44
	v_add_u32_e32 v44, s4, v44
	v_add_u32_e32 v45, 0x420, v44
	v_add_u32_e32 v46, 0x840, v44
	v_add_u32_e32 v47, 0xc60, v44
	v_add_u32_e32 v48, 0x1080, v44
	v_add_u32_e32 v49, 0x14a0, v44
	v_add_u32_e32 v50, 0x18c0, v44
	v_add_u32_e32 v51, 0x1ce0, v44
	v_mul_u32_u24_e32 v52, 0x420, v56
	v_lshl_add_u32 v52, v55, 2, v52
	v_add_u32_e32 v52, s4, v52
	s_add_u32 s78, s52, 0x6d00000
	s_addc_u32 s79, s53, 0
	v_lshrrev_b32_e32 v55, 3, v146
	v_and_b32_e32 v56, 7, v146
	s_mov_b32 s4, 0x2000
	v_mul_lo_u32 v53, v55, s4
	v_lshl_add_u32 v53, v56, 4, v53
	s_mov_b32 s4, 0x800
	v_mul_lo_u32 v54, v55, s4
	v_lshl_add_u32 v54, v56, 4, v54
	s_mov_b32 s0, s3
	s_cmp_ge_u32 s0, 0x400
	s_cbranch_scc1 .Lcv_done_p4br1
	s_lshr_b32 s9, s0, 6
	s_and_b32 s10, s0, 63
	s_lshl_b32 s5, s10, 5
	s_mul_i32 s6, s9, 0x80000
	s_lshl_b32 s5, s5, 2
	s_add_u32 s6, s6, s5
	s_add_u32 s12, s72, s6
	s_addc_u32 s13, s73, 0
	global_load_dwordx4 v[64:67], v53, s[12:13] nt
	s_add_u32 s12, s12, 0x10000
	s_addc_u32 s13, s13, 0
	global_load_dwordx4 v[68:71], v53, s[12:13] nt
	s_add_u32 s12, s12, 0x10000
	s_addc_u32 s13, s13, 0
	global_load_dwordx4 v[72:75], v53, s[12:13] nt
	s_add_u32 s12, s12, 0x10000
	s_addc_u32 s13, s13, 0
	global_load_dwordx4 v[76:79], v53, s[12:13] nt
	s_add_u32 s12, s12, 0x10000
	s_addc_u32 s13, s13, 0
	global_load_dwordx4 v[80:83], v53, s[12:13] nt
	s_add_u32 s12, s12, 0x10000
	s_addc_u32 s13, s13, 0
	global_load_dwordx4 v[84:87], v53, s[12:13] nt
	s_add_u32 s12, s12, 0x10000
	s_addc_u32 s13, s13, 0
	global_load_dwordx4 v[88:91], v53, s[12:13] nt
	s_add_u32 s12, s12, 0x10000
	s_addc_u32 s13, s13, 0
	global_load_dwordx4 v[92:95], v53, s[12:13] nt
	s_add_u32 s1, s0, s8
	s_cmp_ge_u32 s1, 0x400
	s_cbranch_scc1 .Lcv_only1_p4br1
	s_lshr_b32 s9, s1, 6
	s_and_b32 s10, s1, 63
	s_lshl_b32 s5, s10, 5
	s_mul_i32 s6, s9, 0x80000
	s_lshl_b32 s5, s5, 2
	s_add_u32 s6, s6, s5
	s_add_u32 s12, s72, s6
	s_addc_u32 s13, s73, 0
	global_load_dwordx4 v[96:99], v53, s[12:13] nt
	s_add_u32 s12, s12, 0x10000
	s_addc_u32 s13, s13, 0
	global_load_dwordx4 v[100:103], v53, s[12:13] nt
	s_add_u32 s12, s12, 0x10000
	s_addc_u32 s13, s13, 0
	global_load_dwordx4 v[104:107], v53, s[12:13] nt
	s_add_u32 s12, s12, 0x10000
	s_addc_u32 s13, s13, 0
	global_load_dwordx4 v[108:111], v53, s[12:13] nt
	s_add_u32 s12, s12, 0x10000
	s_addc_u32 s13, s13, 0
	global_load_dwordx4 v[112:115], v53, s[12:13] nt
	s_add_u32 s12, s12, 0x10000
	s_addc_u32 s13, s13, 0
	global_load_dwordx4 v[116:119], v53, s[12:13] nt
	s_add_u32 s12, s12, 0x10000
	s_addc_u32 s13, s13, 0
	global_load_dwordx4 v[120:123], v53, s[12:13] nt
	s_add_u32 s12, s12, 0x10000
	s_addc_u32 s13, s13, 0
	global_load_dwordx4 v[124:127], v53, s[12:13] nt
	s_waitcnt vmcnt(8)
	s_branch .Lcv_procA_p4br1

.Lcv_procA_p4br1:
	s_lshr_b32 s9, s0, 6
	s_and_b32 s10, s0, 63
	ds_write2_b32 v44, v64, v65 offset1:1
	ds_write2_b32 v44, v66, v67 offset0:2 offset1:3
	ds_write2_b32 v45, v68, v69 offset1:1
	ds_write2_b32 v45, v70, v71 offset0:2 offset1:3
	ds_write2_b32 v46, v72, v73 offset1:1
	ds_write2_b32 v46, v74, v75 offset0:2 offset1:3
	ds_write2_b32 v47, v76, v77 offset1:1
	ds_write2_b32 v47, v78, v79 offset0:2 offset1:3
	ds_write2_b32 v48, v80, v81 offset1:1
	ds_write2_b32 v48, v82, v83 offset0:2 offset1:3
	ds_write2_b32 v49, v84, v85 offset1:1
	ds_write2_b32 v49, v86, v87 offset0:2 offset1:3
	ds_write2_b32 v50, v88, v89 offset1:1
	ds_write2_b32 v50, v90, v91 offset0:2 offset1:3
	ds_write2_b32 v51, v92, v93 offset1:1
	ds_write2_b32 v51, v94, v95 offset0:2 offset1:3
	s_mul_i32 s5, s10, 0x10000
	s_lshl_b32 s6, s9, 7
	s_add_u32 s5, s5, s6
	s_add_u32 s76, s78, s5
	s_addc_u32 s77, s79, 0
	s_waitcnt lgkmcnt(0)
	ds_read2_b32 v[8:9], v52 offset0:0 offset1:33
	ds_read2_b32 v[10:11], v52 offset0:66 offset1:99
	ds_read2_b32 v[12:13], v52 offset0:132 offset1:165
	ds_read2_b32 v[14:15], v52 offset0:198 offset1:231
	ds_read2_b32 v[16:17], v52 offset0:8 offset1:41
	ds_read2_b32 v[18:19], v52 offset0:74 offset1:107
	ds_read2_b32 v[20:21], v52 offset0:140 offset1:173
	ds_read2_b32 v[22:23], v52 offset0:206 offset1:239
	ds_read2_b32 v[24:25], v52 offset0:16 offset1:49
	ds_read2_b32 v[26:27], v52 offset0:82 offset1:115
	ds_read2_b32 v[28:29], v52 offset0:148 offset1:181
	ds_read2_b32 v[30:31], v52 offset0:214 offset1:247
	ds_read2_b32 v[32:33], v52 offset0:24 offset1:57
	ds_read2_b32 v[34:35], v52 offset0:90 offset1:123
	ds_read2_b32 v[36:37], v52 offset0:156 offset1:189
	ds_read2_b32 v[38:39], v52 offset0:222 offset1:255
	s_waitcnt lgkmcnt(12)
	v_cvt_pk_bf16_f32 v128, v8, v9
	v_cvt_pk_bf16_f32 v129, v10, v11
	v_cvt_pk_bf16_f32 v130, v12, v13
	v_cvt_pk_bf16_f32 v131, v14, v15
	global_store_dwordx4 v54, v[128:131], s[76:77] nt
	s_add_u32 s76, s76, 0x4000
	s_addc_u32 s77, s77, 0
	s_waitcnt lgkmcnt(8)
	v_cvt_pk_bf16_f32 v132, v16, v17
	v_cvt_pk_bf16_f32 v133, v18, v19
	v_cvt_pk_bf16_f32 v134, v20, v21
	v_cvt_pk_bf16_f32 v135, v22, v23
	global_store_dwordx4 v54, v[132:135], s[76:77] nt
	s_add_u32 s76, s76, 0x4000
	s_addc_u32 s77, s77, 0
	s_waitcnt lgkmcnt(4)
	v_cvt_pk_bf16_f32 v136, v24, v25
	v_cvt_pk_bf16_f32 v137, v26, v27
	v_cvt_pk_bf16_f32 v138, v28, v29
	v_cvt_pk_bf16_f32 v139, v30, v31
	global_store_dwordx4 v54, v[136:139], s[76:77] nt
	s_add_u32 s76, s76, 0x4000
	s_addc_u32 s77, s77, 0
	s_waitcnt lgkmcnt(0)
	v_cvt_pk_bf16_f32 v140, v32, v33
	v_cvt_pk_bf16_f32 v141, v34, v35
	v_cvt_pk_bf16_f32 v142, v36, v37
	v_cvt_pk_bf16_f32 v143, v38, v39
	global_store_dwordx4 v54, v[140:143], s[76:77] nt
	s_cmp_ge_u32 s1, 0x400
	s_cbranch_scc1 .Lcv_done_p4br1
	s_add_u32 s0, s1, s8
	s_cmp_ge_u32 s0, 0x400
	s_cbranch_scc1 .Lcv_tailB_p4br1
	s_lshr_b32 s9, s0, 6
	s_and_b32 s10, s0, 63
	s_lshl_b32 s5, s10, 5
	s_mul_i32 s6, s9, 0x80000
	s_lshl_b32 s5, s5, 2
	s_add_u32 s6, s6, s5
	s_add_u32 s12, s72, s6
	s_addc_u32 s13, s73, 0
	global_load_dwordx4 v[64:67], v53, s[12:13] nt
	s_add_u32 s12, s12, 0x10000
	s_addc_u32 s13, s13, 0
	global_load_dwordx4 v[68:71], v53, s[12:13] nt
	s_add_u32 s12, s12, 0x10000
	s_addc_u32 s13, s13, 0
	global_load_dwordx4 v[72:75], v53, s[12:13] nt
	s_add_u32 s12, s12, 0x10000
	s_addc_u32 s13, s13, 0
	global_load_dwordx4 v[76:79], v53, s[12:13] nt
	s_add_u32 s12, s12, 0x10000
	s_addc_u32 s13, s13, 0
	global_load_dwordx4 v[80:83], v53, s[12:13] nt
	s_add_u32 s12, s12, 0x10000
	s_addc_u32 s13, s13, 0
	global_load_dwordx4 v[84:87], v53, s[12:13] nt
	s_add_u32 s12, s12, 0x10000
	s_addc_u32 s13, s13, 0
	global_load_dwordx4 v[88:91], v53, s[12:13] nt
	s_add_u32 s12, s12, 0x10000
	s_addc_u32 s13, s13, 0
	global_load_dwordx4 v[92:95], v53, s[12:13] nt
	s_waitcnt vmcnt(12)
	s_branch .Lcv_procB_p4br1

.Lcv_procB_p4br1:
	s_lshr_b32 s9, s1, 6
	s_and_b32 s10, s1, 63
	ds_write2_b32 v44, v96, v97 offset1:1
	ds_write2_b32 v44, v98, v99 offset0:2 offset1:3
	ds_write2_b32 v45, v100, v101 offset1:1
	ds_write2_b32 v45, v102, v103 offset0:2 offset1:3
	ds_write2_b32 v46, v104, v105 offset1:1
	ds_write2_b32 v46, v106, v107 offset0:2 offset1:3
	ds_write2_b32 v47, v108, v109 offset1:1
	ds_write2_b32 v47, v110, v111 offset0:2 offset1:3
	ds_write2_b32 v48, v112, v113 offset1:1
	ds_write2_b32 v48, v114, v115 offset0:2 offset1:3
	ds_write2_b32 v49, v116, v117 offset1:1
	ds_write2_b32 v49, v118, v119 offset0:2 offset1:3
	ds_write2_b32 v50, v120, v121 offset1:1
	ds_write2_b32 v50, v122, v123 offset0:2 offset1:3
	ds_write2_b32 v51, v124, v125 offset1:1
	ds_write2_b32 v51, v126, v127 offset0:2 offset1:3
	s_mul_i32 s5, s10, 0x10000
	s_lshl_b32 s6, s9, 7
	s_add_u32 s5, s5, s6
	s_add_u32 s76, s78, s5
	s_addc_u32 s77, s79, 0
	s_waitcnt lgkmcnt(0)
	ds_read2_b32 v[8:9], v52 offset0:0 offset1:33
	ds_read2_b32 v[10:11], v52 offset0:66 offset1:99
	ds_read2_b32 v[12:13], v52 offset0:132 offset1:165
	ds_read2_b32 v[14:15], v52 offset0:198 offset1:231
	ds_read2_b32 v[16:17], v52 offset0:8 offset1:41
	ds_read2_b32 v[18:19], v52 offset0:74 offset1:107
	ds_read2_b32 v[20:21], v52 offset0:140 offset1:173
	ds_read2_b32 v[22:23], v52 offset0:206 offset1:239
	ds_read2_b32 v[24:25], v52 offset0:16 offset1:49
	ds_read2_b32 v[26:27], v52 offset0:82 offset1:115
	ds_read2_b32 v[28:29], v52 offset0:148 offset1:181
	ds_read2_b32 v[30:31], v52 offset0:214 offset1:247
	ds_read2_b32 v[32:33], v52 offset0:24 offset1:57
	ds_read2_b32 v[34:35], v52 offset0:90 offset1:123
	ds_read2_b32 v[36:37], v52 offset0:156 offset1:189
	ds_read2_b32 v[38:39], v52 offset0:222 offset1:255
	s_waitcnt lgkmcnt(12)
	v_cvt_pk_bf16_f32 v128, v8, v9
	v_cvt_pk_bf16_f32 v129, v10, v11
	v_cvt_pk_bf16_f32 v130, v12, v13
	v_cvt_pk_bf16_f32 v131, v14, v15
	global_store_dwordx4 v54, v[128:131], s[76:77] nt
	s_add_u32 s76, s76, 0x4000
	s_addc_u32 s77, s77, 0
	s_waitcnt lgkmcnt(8)
	v_cvt_pk_bf16_f32 v132, v16, v17
	v_cvt_pk_bf16_f32 v133, v18, v19
	v_cvt_pk_bf16_f32 v134, v20, v21
	v_cvt_pk_bf16_f32 v135, v22, v23
	global_store_dwordx4 v54, v[132:135], s[76:77] nt
	s_add_u32 s76, s76, 0x4000
	s_addc_u32 s77, s77, 0
	s_waitcnt lgkmcnt(4)
	v_cvt_pk_bf16_f32 v136, v24, v25
	v_cvt_pk_bf16_f32 v137, v26, v27
	v_cvt_pk_bf16_f32 v138, v28, v29
	v_cvt_pk_bf16_f32 v139, v30, v31
	global_store_dwordx4 v54, v[136:139], s[76:77] nt
	s_add_u32 s76, s76, 0x4000
	s_addc_u32 s77, s77, 0
	s_waitcnt lgkmcnt(0)
	v_cvt_pk_bf16_f32 v140, v32, v33
	v_cvt_pk_bf16_f32 v141, v34, v35
	v_cvt_pk_bf16_f32 v142, v36, v37
	v_cvt_pk_bf16_f32 v143, v38, v39
	global_store_dwordx4 v54, v[140:143], s[76:77] nt
	s_cmp_ge_u32 s0, 0x400
	s_cbranch_scc1 .Lcv_done_p4br1
	s_add_u32 s1, s0, s8
	s_cmp_ge_u32 s1, 0x400
	s_cbranch_scc1 .Lcv_tailA_p4br1
	s_lshr_b32 s9, s1, 6
	s_and_b32 s10, s1, 63
	s_lshl_b32 s5, s10, 5
	s_mul_i32 s6, s9, 0x80000
	s_lshl_b32 s5, s5, 2
	s_add_u32 s6, s6, s5
	s_add_u32 s12, s72, s6
	s_addc_u32 s13, s73, 0
	global_load_dwordx4 v[96:99], v53, s[12:13] nt
	s_add_u32 s12, s12, 0x10000
	s_addc_u32 s13, s13, 0
	global_load_dwordx4 v[100:103], v53, s[12:13] nt
	s_add_u32 s12, s12, 0x10000
	s_addc_u32 s13, s13, 0
	global_load_dwordx4 v[104:107], v53, s[12:13] nt
	s_add_u32 s12, s12, 0x10000
	s_addc_u32 s13, s13, 0
	global_load_dwordx4 v[108:111], v53, s[12:13] nt
	s_add_u32 s12, s12, 0x10000
	s_addc_u32 s13, s13, 0
	global_load_dwordx4 v[112:115], v53, s[12:13] nt
	s_add_u32 s12, s12, 0x10000
	s_addc_u32 s13, s13, 0
	global_load_dwordx4 v[116:119], v53, s[12:13] nt
	s_add_u32 s12, s12, 0x10000
	s_addc_u32 s13, s13, 0
	global_load_dwordx4 v[120:123], v53, s[12:13] nt
	s_add_u32 s12, s12, 0x10000
	s_addc_u32 s13, s13, 0
	global_load_dwordx4 v[124:127], v53, s[12:13] nt
	s_waitcnt vmcnt(12)
	s_branch .Lcv_procA_p4br1

.Lcv_done_p4br1:
	s_add_u32 s78, s52, 0x7100000
	s_addc_u32 s79, s53, 0
	s_add_u32 s90, s72, 0x800000
	s_addc_u32 s91, s73, 0
	v_lshrrev_b32_e32 v55, 3, v146
	v_and_b32_e32 v56, 7, v146
	s_mov_b32 s4, 0x2000
	v_mul_lo_u32 v53, v55, s4
	v_lshl_add_u32 v53, v56, 4, v53
	s_mov_b32 s4, 0x800
	v_mul_lo_u32 v54, v55, s4
	v_lshl_add_u32 v54, v56, 4, v54
	s_mov_b32 s0, s3
	s_cmp_ge_u32 s0, 0x400
	s_cbranch_scc1 .Lcv_done_p4br2
	s_lshr_b32 s9, s0, 6
	s_and_b32 s10, s0, 63
	s_lshl_b32 s5, s10, 5
	s_mul_i32 s6, s9, 0x80000
	s_lshl_b32 s5, s5, 2
	s_add_u32 s6, s6, s5
	s_add_u32 s12, s90, s6
	s_addc_u32 s13, s91, 0
	global_load_dwordx4 v[64:67], v53, s[12:13] nt
	s_add_u32 s12, s12, 0x10000
	s_addc_u32 s13, s13, 0
	global_load_dwordx4 v[68:71], v53, s[12:13] nt
	s_add_u32 s12, s12, 0x10000
	s_addc_u32 s13, s13, 0
	global_load_dwordx4 v[72:75], v53, s[12:13] nt
	s_add_u32 s12, s12, 0x10000
	s_addc_u32 s13, s13, 0
	global_load_dwordx4 v[76:79], v53, s[12:13] nt
	s_add_u32 s12, s12, 0x10000
	s_addc_u32 s13, s13, 0
	global_load_dwordx4 v[80:83], v53, s[12:13] nt
	s_add_u32 s12, s12, 0x10000
	s_addc_u32 s13, s13, 0
	global_load_dwordx4 v[84:87], v53, s[12:13] nt
	s_add_u32 s12, s12, 0x10000
	s_addc_u32 s13, s13, 0
	global_load_dwordx4 v[88:91], v53, s[12:13] nt
	s_add_u32 s12, s12, 0x10000
	s_addc_u32 s13, s13, 0
	global_load_dwordx4 v[92:95], v53, s[12:13] nt
	s_add_u32 s1, s0, s8
	s_cmp_ge_u32 s1, 0x400
	s_cbranch_scc1 .Lcv_only1_p4br2
	s_lshr_b32 s9, s1, 6
	s_and_b32 s10, s1, 63
	s_lshl_b32 s5, s10, 5
	s_mul_i32 s6, s9, 0x80000
	s_lshl_b32 s5, s5, 2
	s_add_u32 s6, s6, s5
	s_add_u32 s12, s90, s6
	s_addc_u32 s13, s91, 0
	global_load_dwordx4 v[96:99], v53, s[12:13] nt
	s_add_u32 s12, s12, 0x10000
	s_addc_u32 s13, s13, 0
	global_load_dwordx4 v[100:103], v53, s[12:13] nt
	s_add_u32 s12, s12, 0x10000
	s_addc_u32 s13, s13, 0
	global_load_dwordx4 v[104:107], v53, s[12:13] nt
	s_add_u32 s12, s12, 0x10000
	s_addc_u32 s13, s13, 0
	global_load_dwordx4 v[108:111], v53, s[12:13] nt
	s_add_u32 s12, s12, 0x10000
	s_addc_u32 s13, s13, 0
	global_load_dwordx4 v[112:115], v53, s[12:13] nt
	s_add_u32 s12, s12, 0x10000
	s_addc_u32 s13, s13, 0
	global_load_dwordx4 v[116:119], v53, s[12:13] nt
	s_add_u32 s12, s12, 0x10000
	s_addc_u32 s13, s13, 0
	global_load_dwordx4 v[120:123], v53, s[12:13] nt
	s_add_u32 s12, s12, 0x10000
	s_addc_u32 s13, s13, 0
	global_load_dwordx4 v[124:127], v53, s[12:13] nt
	s_waitcnt vmcnt(8)
	s_branch .Lcv_procA_p4br2

.Lcv_procA_p4br2:
	s_lshr_b32 s9, s0, 6
	s_and_b32 s10, s0, 63
	ds_write2_b32 v44, v64, v65 offset1:1
	ds_write2_b32 v44, v66, v67 offset0:2 offset1:3
	ds_write2_b32 v45, v68, v69 offset1:1
	ds_write2_b32 v45, v70, v71 offset0:2 offset1:3
	ds_write2_b32 v46, v72, v73 offset1:1
	ds_write2_b32 v46, v74, v75 offset0:2 offset1:3
	ds_write2_b32 v47, v76, v77 offset1:1
	ds_write2_b32 v47, v78, v79 offset0:2 offset1:3
	ds_write2_b32 v48, v80, v81 offset1:1
	ds_write2_b32 v48, v82, v83 offset0:2 offset1:3
	ds_write2_b32 v49, v84, v85 offset1:1
	ds_write2_b32 v49, v86, v87 offset0:2 offset1:3
	ds_write2_b32 v50, v88, v89 offset1:1
	ds_write2_b32 v50, v90, v91 offset0:2 offset1:3
	ds_write2_b32 v51, v92, v93 offset1:1
	ds_write2_b32 v51, v94, v95 offset0:2 offset1:3
	s_mul_i32 s5, s10, 0x10000
	s_lshl_b32 s6, s9, 7
	s_add_u32 s5, s5, s6
	s_add_u32 s76, s78, s5
	s_addc_u32 s77, s79, 0
	s_waitcnt lgkmcnt(0)
	ds_read2_b32 v[8:9], v52 offset0:0 offset1:33
	ds_read2_b32 v[10:11], v52 offset0:66 offset1:99
	ds_read2_b32 v[12:13], v52 offset0:132 offset1:165
	ds_read2_b32 v[14:15], v52 offset0:198 offset1:231
	ds_read2_b32 v[16:17], v52 offset0:8 offset1:41
	ds_read2_b32 v[18:19], v52 offset0:74 offset1:107
	ds_read2_b32 v[20:21], v52 offset0:140 offset1:173
	ds_read2_b32 v[22:23], v52 offset0:206 offset1:239
	ds_read2_b32 v[24:25], v52 offset0:16 offset1:49
	ds_read2_b32 v[26:27], v52 offset0:82 offset1:115
	ds_read2_b32 v[28:29], v52 offset0:148 offset1:181
	ds_read2_b32 v[30:31], v52 offset0:214 offset1:247
	ds_read2_b32 v[32:33], v52 offset0:24 offset1:57
	ds_read2_b32 v[34:35], v52 offset0:90 offset1:123
	ds_read2_b32 v[36:37], v52 offset0:156 offset1:189
	ds_read2_b32 v[38:39], v52 offset0:222 offset1:255
	s_waitcnt lgkmcnt(12)
	v_cvt_pk_bf16_f32 v128, v8, v9
	v_cvt_pk_bf16_f32 v129, v10, v11
	v_cvt_pk_bf16_f32 v130, v12, v13
	v_cvt_pk_bf16_f32 v131, v14, v15
	global_store_dwordx4 v54, v[128:131], s[76:77] nt
	s_add_u32 s76, s76, 0x4000
	s_addc_u32 s77, s77, 0
	s_waitcnt lgkmcnt(8)
	v_cvt_pk_bf16_f32 v132, v16, v17
	v_cvt_pk_bf16_f32 v133, v18, v19
	v_cvt_pk_bf16_f32 v134, v20, v21
	v_cvt_pk_bf16_f32 v135, v22, v23
	global_store_dwordx4 v54, v[132:135], s[76:77] nt
	s_add_u32 s76, s76, 0x4000
	s_addc_u32 s77, s77, 0
	s_waitcnt lgkmcnt(4)
	v_cvt_pk_bf16_f32 v136, v24, v25
	v_cvt_pk_bf16_f32 v137, v26, v27
	v_cvt_pk_bf16_f32 v138, v28, v29
	v_cvt_pk_bf16_f32 v139, v30, v31
	global_store_dwordx4 v54, v[136:139], s[76:77] nt
	s_add_u32 s76, s76, 0x4000
	s_addc_u32 s77, s77, 0
	s_waitcnt lgkmcnt(0)
	v_cvt_pk_bf16_f32 v140, v32, v33
	v_cvt_pk_bf16_f32 v141, v34, v35
	v_cvt_pk_bf16_f32 v142, v36, v37
	v_cvt_pk_bf16_f32 v143, v38, v39
	global_store_dwordx4 v54, v[140:143], s[76:77] nt
	s_cmp_ge_u32 s1, 0x400
	s_cbranch_scc1 .Lcv_done_p4br2
	s_add_u32 s0, s1, s8
	s_cmp_ge_u32 s0, 0x400
	s_cbranch_scc1 .Lcv_tailB_p4br2
	s_lshr_b32 s9, s0, 6
	s_and_b32 s10, s0, 63
	s_lshl_b32 s5, s10, 5
	s_mul_i32 s6, s9, 0x80000
	s_lshl_b32 s5, s5, 2
	s_add_u32 s6, s6, s5
	s_add_u32 s12, s90, s6
	s_addc_u32 s13, s91, 0
	global_load_dwordx4 v[64:67], v53, s[12:13] nt
	s_add_u32 s12, s12, 0x10000
	s_addc_u32 s13, s13, 0
	global_load_dwordx4 v[68:71], v53, s[12:13] nt
	s_add_u32 s12, s12, 0x10000
	s_addc_u32 s13, s13, 0
	global_load_dwordx4 v[72:75], v53, s[12:13] nt
	s_add_u32 s12, s12, 0x10000
	s_addc_u32 s13, s13, 0
	global_load_dwordx4 v[76:79], v53, s[12:13] nt
	s_add_u32 s12, s12, 0x10000
	s_addc_u32 s13, s13, 0
	global_load_dwordx4 v[80:83], v53, s[12:13] nt
	s_add_u32 s12, s12, 0x10000
	s_addc_u32 s13, s13, 0
	global_load_dwordx4 v[84:87], v53, s[12:13] nt
	s_add_u32 s12, s12, 0x10000
	s_addc_u32 s13, s13, 0
	global_load_dwordx4 v[88:91], v53, s[12:13] nt
	s_add_u32 s12, s12, 0x10000
	s_addc_u32 s13, s13, 0
	global_load_dwordx4 v[92:95], v53, s[12:13] nt
	s_waitcnt vmcnt(12)
	s_branch .Lcv_procB_p4br2

.Lcv_procB_p4br2:
	s_lshr_b32 s9, s1, 6
	s_and_b32 s10, s1, 63
	ds_write2_b32 v44, v96, v97 offset1:1
	ds_write2_b32 v44, v98, v99 offset0:2 offset1:3
	ds_write2_b32 v45, v100, v101 offset1:1
	ds_write2_b32 v45, v102, v103 offset0:2 offset1:3
	ds_write2_b32 v46, v104, v105 offset1:1
	ds_write2_b32 v46, v106, v107 offset0:2 offset1:3
	ds_write2_b32 v47, v108, v109 offset1:1
	ds_write2_b32 v47, v110, v111 offset0:2 offset1:3
	ds_write2_b32 v48, v112, v113 offset1:1
	ds_write2_b32 v48, v114, v115 offset0:2 offset1:3
	ds_write2_b32 v49, v116, v117 offset1:1
	ds_write2_b32 v49, v118, v119 offset0:2 offset1:3
	ds_write2_b32 v50, v120, v121 offset1:1
	ds_write2_b32 v50, v122, v123 offset0:2 offset1:3
	ds_write2_b32 v51, v124, v125 offset1:1
	ds_write2_b32 v51, v126, v127 offset0:2 offset1:3
	s_mul_i32 s5, s10, 0x10000
	s_lshl_b32 s6, s9, 7
	s_add_u32 s5, s5, s6
	s_add_u32 s76, s78, s5
	s_addc_u32 s77, s79, 0
	s_waitcnt lgkmcnt(0)
	ds_read2_b32 v[8:9], v52 offset0:0 offset1:33
	ds_read2_b32 v[10:11], v52 offset0:66 offset1:99
	ds_read2_b32 v[12:13], v52 offset0:132 offset1:165
	ds_read2_b32 v[14:15], v52 offset0:198 offset1:231
	ds_read2_b32 v[16:17], v52 offset0:8 offset1:41
	ds_read2_b32 v[18:19], v52 offset0:74 offset1:107
	ds_read2_b32 v[20:21], v52 offset0:140 offset1:173
	ds_read2_b32 v[22:23], v52 offset0:206 offset1:239
	ds_read2_b32 v[24:25], v52 offset0:16 offset1:49
	ds_read2_b32 v[26:27], v52 offset0:82 offset1:115
	ds_read2_b32 v[28:29], v52 offset0:148 offset1:181
	ds_read2_b32 v[30:31], v52 offset0:214 offset1:247
	ds_read2_b32 v[32:33], v52 offset0:24 offset1:57
	ds_read2_b32 v[34:35], v52 offset0:90 offset1:123
	ds_read2_b32 v[36:37], v52 offset0:156 offset1:189
	ds_read2_b32 v[38:39], v52 offset0:222 offset1:255
	s_waitcnt lgkmcnt(12)
	v_cvt_pk_bf16_f32 v128, v8, v9
	v_cvt_pk_bf16_f32 v129, v10, v11
	v_cvt_pk_bf16_f32 v130, v12, v13
	v_cvt_pk_bf16_f32 v131, v14, v15
	global_store_dwordx4 v54, v[128:131], s[76:77] nt
	s_add_u32 s76, s76, 0x4000
	s_addc_u32 s77, s77, 0
	s_waitcnt lgkmcnt(8)
	v_cvt_pk_bf16_f32 v132, v16, v17
	v_cvt_pk_bf16_f32 v133, v18, v19
	v_cvt_pk_bf16_f32 v134, v20, v21
	v_cvt_pk_bf16_f32 v135, v22, v23
	global_store_dwordx4 v54, v[132:135], s[76:77] nt
	s_add_u32 s76, s76, 0x4000
	s_addc_u32 s77, s77, 0
	s_waitcnt lgkmcnt(4)
	v_cvt_pk_bf16_f32 v136, v24, v25
	v_cvt_pk_bf16_f32 v137, v26, v27
	v_cvt_pk_bf16_f32 v138, v28, v29
	v_cvt_pk_bf16_f32 v139, v30, v31
	global_store_dwordx4 v54, v[136:139], s[76:77] nt
	s_add_u32 s76, s76, 0x4000
	s_addc_u32 s77, s77, 0
	s_waitcnt lgkmcnt(0)
	v_cvt_pk_bf16_f32 v140, v32, v33
	v_cvt_pk_bf16_f32 v141, v34, v35
	v_cvt_pk_bf16_f32 v142, v36, v37
	v_cvt_pk_bf16_f32 v143, v38, v39
	global_store_dwordx4 v54, v[140:143], s[76:77] nt
	s_cmp_ge_u32 s0, 0x400
	s_cbranch_scc1 .Lcv_done_p4br2
	s_add_u32 s1, s0, s8
	s_cmp_ge_u32 s1, 0x400
	s_cbranch_scc1 .Lcv_tailA_p4br2
	s_lshr_b32 s9, s1, 6
	s_and_b32 s10, s1, 63
	s_lshl_b32 s5, s10, 5
	s_mul_i32 s6, s9, 0x80000
	s_lshl_b32 s5, s5, 2
	s_add_u32 s6, s6, s5
	s_add_u32 s12, s90, s6
	s_addc_u32 s13, s91, 0
	global_load_dwordx4 v[96:99], v53, s[12:13] nt
	s_add_u32 s12, s12, 0x10000
	s_addc_u32 s13, s13, 0
	global_load_dwordx4 v[100:103], v53, s[12:13] nt
	s_add_u32 s12, s12, 0x10000
	s_addc_u32 s13, s13, 0
	global_load_dwordx4 v[104:107], v53, s[12:13] nt
	s_add_u32 s12, s12, 0x10000
	s_addc_u32 s13, s13, 0
	global_load_dwordx4 v[108:111], v53, s[12:13] nt
	s_add_u32 s12, s12, 0x10000
	s_addc_u32 s13, s13, 0
	global_load_dwordx4 v[112:115], v53, s[12:13] nt
	s_add_u32 s12, s12, 0x10000
	s_addc_u32 s13, s13, 0
	global_load_dwordx4 v[116:119], v53, s[12:13] nt
	s_add_u32 s12, s12, 0x10000
	s_addc_u32 s13, s13, 0
	global_load_dwordx4 v[120:123], v53, s[12:13] nt
	s_add_u32 s12, s12, 0x10000
	s_addc_u32 s13, s13, 0
	global_load_dwordx4 v[124:127], v53, s[12:13] nt
	s_waitcnt vmcnt(12)
	s_branch .Lcv_procA_p4br2

.Lcv_done_p4br2:
	s_add_u32 s78, s52, 0x7500000
	s_addc_u32 s79, s53, 0
	v_lshrrev_b32_e32 v55, 3, v146
	v_and_b32_e32 v56, 7, v146
	s_mov_b32 s4, 0x2000
	v_mul_lo_u32 v53, v55, s4
	v_lshl_add_u32 v53, v56, 4, v53
	s_mov_b32 s4, 0x1000
	v_mul_lo_u32 v54, v55, s4
	v_lshl_add_u32 v54, v56, 4, v54
	s_mov_b32 s0, s3
	s_cmp_ge_u32 s0, 0x800
	s_cbranch_scc1 .Lcv_done_p4out
	s_lshr_b32 s9, s0, 6
	s_and_b32 s10, s0, 63
	s_lshl_b32 s5, s10, 5
	s_mul_i32 s6, s9, 0x80000
	s_lshl_b32 s5, s5, 2
	s_add_u32 s6, s6, s5
	s_add_u32 s12, s74, s6
	s_addc_u32 s13, s75, 0
	global_load_dwordx4 v[64:67], v53, s[12:13] nt
	s_add_u32 s12, s12, 0x10000
	s_addc_u32 s13, s13, 0
	global_load_dwordx4 v[68:71], v53, s[12:13] nt
	s_add_u32 s12, s12, 0x10000
	s_addc_u32 s13, s13, 0
	global_load_dwordx4 v[72:75], v53, s[12:13] nt
	s_add_u32 s12, s12, 0x10000
	s_addc_u32 s13, s13, 0
	global_load_dwordx4 v[76:79], v53, s[12:13] nt
	s_add_u32 s12, s12, 0x10000
	s_addc_u32 s13, s13, 0
	global_load_dwordx4 v[80:83], v53, s[12:13] nt
	s_add_u32 s12, s12, 0x10000
	s_addc_u32 s13, s13, 0
	global_load_dwordx4 v[84:87], v53, s[12:13] nt
	s_add_u32 s12, s12, 0x10000
	s_addc_u32 s13, s13, 0
	global_load_dwordx4 v[88:91], v53, s[12:13] nt
	s_add_u32 s12, s12, 0x10000
	s_addc_u32 s13, s13, 0
	global_load_dwordx4 v[92:95], v53, s[12:13] nt
	s_add_u32 s1, s0, s8
	s_cmp_ge_u32 s1, 0x800
	s_cbranch_scc1 .Lcv_only1_p4out
	s_lshr_b32 s9, s1, 6
	s_and_b32 s10, s1, 63
	s_lshl_b32 s5, s10, 5
	s_mul_i32 s6, s9, 0x80000
	s_lshl_b32 s5, s5, 2
	s_add_u32 s6, s6, s5
	s_add_u32 s12, s74, s6
	s_addc_u32 s13, s75, 0
	global_load_dwordx4 v[96:99], v53, s[12:13] nt
	s_add_u32 s12, s12, 0x10000
	s_addc_u32 s13, s13, 0
	global_load_dwordx4 v[100:103], v53, s[12:13] nt
	s_add_u32 s12, s12, 0x10000
	s_addc_u32 s13, s13, 0
	global_load_dwordx4 v[104:107], v53, s[12:13] nt
	s_add_u32 s12, s12, 0x10000
	s_addc_u32 s13, s13, 0
	global_load_dwordx4 v[108:111], v53, s[12:13] nt
	s_add_u32 s12, s12, 0x10000
	s_addc_u32 s13, s13, 0
	global_load_dwordx4 v[112:115], v53, s[12:13] nt
	s_add_u32 s12, s12, 0x10000
	s_addc_u32 s13, s13, 0
	global_load_dwordx4 v[116:119], v53, s[12:13] nt
	s_add_u32 s12, s12, 0x10000
	s_addc_u32 s13, s13, 0
	global_load_dwordx4 v[120:123], v53, s[12:13] nt
	s_add_u32 s12, s12, 0x10000
	s_addc_u32 s13, s13, 0
	global_load_dwordx4 v[124:127], v53, s[12:13] nt
	s_waitcnt vmcnt(8)
	s_branch .Lcv_procA_p4out

.Lcv_procA_p4out:
	s_lshr_b32 s9, s0, 6
	s_and_b32 s10, s0, 63
	ds_write2_b32 v44, v64, v65 offset1:1
	ds_write2_b32 v44, v66, v67 offset0:2 offset1:3
	ds_write2_b32 v45, v68, v69 offset1:1
	ds_write2_b32 v45, v70, v71 offset0:2 offset1:3
	ds_write2_b32 v46, v72, v73 offset1:1
	ds_write2_b32 v46, v74, v75 offset0:2 offset1:3
	ds_write2_b32 v47, v76, v77 offset1:1
	ds_write2_b32 v47, v78, v79 offset0:2 offset1:3
	ds_write2_b32 v48, v80, v81 offset1:1
	ds_write2_b32 v48, v82, v83 offset0:2 offset1:3
	ds_write2_b32 v49, v84, v85 offset1:1
	ds_write2_b32 v49, v86, v87 offset0:2 offset1:3
	ds_write2_b32 v50, v88, v89 offset1:1
	ds_write2_b32 v50, v90, v91 offset0:2 offset1:3
	ds_write2_b32 v51, v92, v93 offset1:1
	ds_write2_b32 v51, v94, v95 offset0:2 offset1:3
	s_mul_i32 s5, s10, 0x20000
	s_lshl_b32 s6, s9, 7
	s_add_u32 s5, s5, s6
	s_add_u32 s76, s78, s5
	s_addc_u32 s77, s79, 0
	s_waitcnt lgkmcnt(0)
	ds_read2_b32 v[8:9], v52 offset0:0 offset1:33
	ds_read2_b32 v[10:11], v52 offset0:66 offset1:99
	ds_read2_b32 v[12:13], v52 offset0:132 offset1:165
	ds_read2_b32 v[14:15], v52 offset0:198 offset1:231
	ds_read2_b32 v[16:17], v52 offset0:8 offset1:41
	ds_read2_b32 v[18:19], v52 offset0:74 offset1:107
	ds_read2_b32 v[20:21], v52 offset0:140 offset1:173
	ds_read2_b32 v[22:23], v52 offset0:206 offset1:239
	ds_read2_b32 v[24:25], v52 offset0:16 offset1:49
	ds_read2_b32 v[26:27], v52 offset0:82 offset1:115
	ds_read2_b32 v[28:29], v52 offset0:148 offset1:181
	ds_read2_b32 v[30:31], v52 offset0:214 offset1:247
	ds_read2_b32 v[32:33], v52 offset0:24 offset1:57
	ds_read2_b32 v[34:35], v52 offset0:90 offset1:123
	ds_read2_b32 v[36:37], v52 offset0:156 offset1:189
	ds_read2_b32 v[38:39], v52 offset0:222 offset1:255
	s_waitcnt lgkmcnt(12)
	v_cvt_pk_bf16_f32 v128, v8, v9
	v_cvt_pk_bf16_f32 v129, v10, v11
	v_cvt_pk_bf16_f32 v130, v12, v13
	v_cvt_pk_bf16_f32 v131, v14, v15
	global_store_dwordx4 v54, v[128:131], s[76:77] nt
	s_add_u32 s76, s76, 0x8000
	s_addc_u32 s77, s77, 0
	s_waitcnt lgkmcnt(8)
	v_cvt_pk_bf16_f32 v132, v16, v17
	v_cvt_pk_bf16_f32 v133, v18, v19
	v_cvt_pk_bf16_f32 v134, v20, v21
	v_cvt_pk_bf16_f32 v135, v22, v23
	global_store_dwordx4 v54, v[132:135], s[76:77] nt
	s_add_u32 s76, s76, 0x8000
	s_addc_u32 s77, s77, 0
	s_waitcnt lgkmcnt(4)
	v_cvt_pk_bf16_f32 v136, v24, v25
	v_cvt_pk_bf16_f32 v137, v26, v27
	v_cvt_pk_bf16_f32 v138, v28, v29
	v_cvt_pk_bf16_f32 v139, v30, v31
	global_store_dwordx4 v54, v[136:139], s[76:77] nt
	s_add_u32 s76, s76, 0x8000
	s_addc_u32 s77, s77, 0
	s_waitcnt lgkmcnt(0)
	v_cvt_pk_bf16_f32 v140, v32, v33
	v_cvt_pk_bf16_f32 v141, v34, v35
	v_cvt_pk_bf16_f32 v142, v36, v37
	v_cvt_pk_bf16_f32 v143, v38, v39
	global_store_dwordx4 v54, v[140:143], s[76:77] nt
	s_cmp_ge_u32 s1, 0x800
	s_cbranch_scc1 .Lcv_done_p4out
	s_add_u32 s0, s1, s8
	s_cmp_ge_u32 s0, 0x800
	s_cbranch_scc1 .Lcv_tailB_p4out
	s_lshr_b32 s9, s0, 6
	s_and_b32 s10, s0, 63
	s_lshl_b32 s5, s10, 5
	s_mul_i32 s6, s9, 0x80000
	s_lshl_b32 s5, s5, 2
	s_add_u32 s6, s6, s5
	s_add_u32 s12, s74, s6
	s_addc_u32 s13, s75, 0
	global_load_dwordx4 v[64:67], v53, s[12:13] nt
	s_add_u32 s12, s12, 0x10000
	s_addc_u32 s13, s13, 0
	global_load_dwordx4 v[68:71], v53, s[12:13] nt
	s_add_u32 s12, s12, 0x10000
	s_addc_u32 s13, s13, 0
	global_load_dwordx4 v[72:75], v53, s[12:13] nt
	s_add_u32 s12, s12, 0x10000
	s_addc_u32 s13, s13, 0
	global_load_dwordx4 v[76:79], v53, s[12:13] nt
	s_add_u32 s12, s12, 0x10000
	s_addc_u32 s13, s13, 0
	global_load_dwordx4 v[80:83], v53, s[12:13] nt
	s_add_u32 s12, s12, 0x10000
	s_addc_u32 s13, s13, 0
	global_load_dwordx4 v[84:87], v53, s[12:13] nt
	s_add_u32 s12, s12, 0x10000
	s_addc_u32 s13, s13, 0
	global_load_dwordx4 v[88:91], v53, s[12:13] nt
	s_add_u32 s12, s12, 0x10000
	s_addc_u32 s13, s13, 0
	global_load_dwordx4 v[92:95], v53, s[12:13] nt
	s_waitcnt vmcnt(12)
	s_branch .Lcv_procB_p4out

.Lcv_procB_p4out:
	s_lshr_b32 s9, s1, 6
	s_and_b32 s10, s1, 63
	ds_write2_b32 v44, v96, v97 offset1:1
	ds_write2_b32 v44, v98, v99 offset0:2 offset1:3
	ds_write2_b32 v45, v100, v101 offset1:1
	ds_write2_b32 v45, v102, v103 offset0:2 offset1:3
	ds_write2_b32 v46, v104, v105 offset1:1
	ds_write2_b32 v46, v106, v107 offset0:2 offset1:3
	ds_write2_b32 v47, v108, v109 offset1:1
	ds_write2_b32 v47, v110, v111 offset0:2 offset1:3
	ds_write2_b32 v48, v112, v113 offset1:1
	ds_write2_b32 v48, v114, v115 offset0:2 offset1:3
	ds_write2_b32 v49, v116, v117 offset1:1
	ds_write2_b32 v49, v118, v119 offset0:2 offset1:3
	ds_write2_b32 v50, v120, v121 offset1:1
	ds_write2_b32 v50, v122, v123 offset0:2 offset1:3
	ds_write2_b32 v51, v124, v125 offset1:1
	ds_write2_b32 v51, v126, v127 offset0:2 offset1:3
	s_mul_i32 s5, s10, 0x20000
	s_lshl_b32 s6, s9, 7
	s_add_u32 s5, s5, s6
	s_add_u32 s76, s78, s5
	s_addc_u32 s77, s79, 0
	s_waitcnt lgkmcnt(0)
	ds_read2_b32 v[8:9], v52 offset0:0 offset1:33
	ds_read2_b32 v[10:11], v52 offset0:66 offset1:99
	ds_read2_b32 v[12:13], v52 offset0:132 offset1:165
	ds_read2_b32 v[14:15], v52 offset0:198 offset1:231
	ds_read2_b32 v[16:17], v52 offset0:8 offset1:41
	ds_read2_b32 v[18:19], v52 offset0:74 offset1:107
	ds_read2_b32 v[20:21], v52 offset0:140 offset1:173
	ds_read2_b32 v[22:23], v52 offset0:206 offset1:239
	ds_read2_b32 v[24:25], v52 offset0:16 offset1:49
	ds_read2_b32 v[26:27], v52 offset0:82 offset1:115
	ds_read2_b32 v[28:29], v52 offset0:148 offset1:181
	ds_read2_b32 v[30:31], v52 offset0:214 offset1:247
	ds_read2_b32 v[32:33], v52 offset0:24 offset1:57
	ds_read2_b32 v[34:35], v52 offset0:90 offset1:123
	ds_read2_b32 v[36:37], v52 offset0:156 offset1:189
	ds_read2_b32 v[38:39], v52 offset0:222 offset1:255
	s_waitcnt lgkmcnt(12)
	v_cvt_pk_bf16_f32 v128, v8, v9
	v_cvt_pk_bf16_f32 v129, v10, v11
	v_cvt_pk_bf16_f32 v130, v12, v13
	v_cvt_pk_bf16_f32 v131, v14, v15
	global_store_dwordx4 v54, v[128:131], s[76:77] nt
	s_add_u32 s76, s76, 0x8000
	s_addc_u32 s77, s77, 0
	s_waitcnt lgkmcnt(8)
	v_cvt_pk_bf16_f32 v132, v16, v17
	v_cvt_pk_bf16_f32 v133, v18, v19
	v_cvt_pk_bf16_f32 v134, v20, v21
	v_cvt_pk_bf16_f32 v135, v22, v23
	global_store_dwordx4 v54, v[132:135], s[76:77] nt
	s_add_u32 s76, s76, 0x8000
	s_addc_u32 s77, s77, 0
	s_waitcnt lgkmcnt(4)
	v_cvt_pk_bf16_f32 v136, v24, v25
	v_cvt_pk_bf16_f32 v137, v26, v27
	v_cvt_pk_bf16_f32 v138, v28, v29
	v_cvt_pk_bf16_f32 v139, v30, v31
	global_store_dwordx4 v54, v[136:139], s[76:77] nt
	s_add_u32 s76, s76, 0x8000
	s_addc_u32 s77, s77, 0
	s_waitcnt lgkmcnt(0)
	v_cvt_pk_bf16_f32 v140, v32, v33
	v_cvt_pk_bf16_f32 v141, v34, v35
	v_cvt_pk_bf16_f32 v142, v36, v37
	v_cvt_pk_bf16_f32 v143, v38, v39
	global_store_dwordx4 v54, v[140:143], s[76:77] nt
	s_cmp_ge_u32 s0, 0x800
	s_cbranch_scc1 .Lcv_done_p4out
	s_add_u32 s1, s0, s8
	s_cmp_ge_u32 s1, 0x800
	s_cbranch_scc1 .Lcv_tailA_p4out
	s_lshr_b32 s9, s1, 6
	s_and_b32 s10, s1, 63
	s_lshl_b32 s5, s10, 5
	s_mul_i32 s6, s9, 0x80000
	s_lshl_b32 s5, s5, 2
	s_add_u32 s6, s6, s5
	s_add_u32 s12, s74, s6
	s_addc_u32 s13, s75, 0
	global_load_dwordx4 v[96:99], v53, s[12:13] nt
	s_add_u32 s12, s12, 0x10000
	s_addc_u32 s13, s13, 0
	global_load_dwordx4 v[100:103], v53, s[12:13] nt
	s_add_u32 s12, s12, 0x10000
	s_addc_u32 s13, s13, 0
	global_load_dwordx4 v[104:107], v53, s[12:13] nt
	s_add_u32 s12, s12, 0x10000
	s_addc_u32 s13, s13, 0
	global_load_dwordx4 v[108:111], v53, s[12:13] nt
	s_add_u32 s12, s12, 0x10000
	s_addc_u32 s13, s13, 0
	global_load_dwordx4 v[112:115], v53, s[12:13] nt
	s_add_u32 s12, s12, 0x10000
	s_addc_u32 s13, s13, 0
	global_load_dwordx4 v[116:119], v53, s[12:13] nt
	s_add_u32 s12, s12, 0x10000
	s_addc_u32 s13, s13, 0
	global_load_dwordx4 v[120:123], v53, s[12:13] nt
	s_add_u32 s12, s12, 0x10000
	s_addc_u32 s13, s13, 0
	global_load_dwordx4 v[124:127], v53, s[12:13] nt
	s_waitcnt vmcnt(12)
	s_branch .Lcv_procA_p4out

.Lcv_done_p4out:
.LBB0_423:
	s_waitcnt vmcnt(0)
	s_barrier
	s_mov_b64 s[0:1], exec
	v_readlane_b32 s4, v240, 9
	v_readlane_b32 s5, v240, 10
	s_and_b64 s[4:5], s[0:1], s[4:5]
	s_mov_b64 exec, s[4:5]
	s_cbranch_execz .LBB0_475
	s_add_i32 s3, 0, 0x23fc0
	v_mov_b32_e32 v0, s3
	s_waitcnt vmcnt(0) expcnt(0) lgkmcnt(0)
	ds_read_b32 v2, v0
	s_add_i32 s3, 0, 0x23fc4
	v_mov_b32_e32 v0, s3
	ds_read_b32 v0, v0
	s_waitcnt lgkmcnt(1)
	v_cmp_ne_u32_e32 vcc, 0, v2
	s_cbranch_vccnz .LBB0_439
	s_add_u32 s4, s52, 0x40200
	s_addc_u32 s5, s53, 0
	s_add_u32 s6, s52, 0x40400
	s_addc_u32 s7, s53, 0
	s_add_u32 s8, s52, 0x40500
	s_addc_u32 s9, s53, 0
	s_add_u32 s12, s52, 0x40600
	s_addc_u32 s13, s53, 0
	s_add_u32 s14, s52, 0x40700
	s_addc_u32 s15, s53, 0
	s_add_u32 s16, s52, 0x40800
	s_addc_u32 s17, s53, 0
	s_add_u32 s18, s52, 0x40900
	s_addc_u32 s19, s53, 0
	s_add_u32 s20, s52, 0x40a00
	s_addc_u32 s21, s53, 0
	s_add_u32 s22, s52, 0x40b00
	s_addc_u32 s23, s53, 0
	s_add_u32 s58, s52, 0x40c00
	s_addc_u32 s59, s53, 0
	s_add_u32 s60, s52, 0x40d00
	s_addc_u32 s61, s53, 0
	s_add_u32 s62, s52, 0x40e00
	s_addc_u32 s63, s53, 0
	s_add_u32 s84, s52, 0x40f00
	s_addc_u32 s85, s53, 0
	s_add_u32 s86, s52, 0x41000
	s_addc_u32 s87, s53, 0
	s_add_u32 s88, s52, 0x41100
	s_addc_u32 s89, s53, 0
	s_add_u32 s10, s52, 0x41200
	v_readlane_b32 s3, v240, 0
	s_addc_u32 s11, s53, 0
	s_mul_i32 s3, s31, s3
	s_add_u32 s28, s52, 0x41300
	s_mul_i32 s3, s3, s30
	s_addc_u32 s29, s53, 0
	s_mov_b32 s35, 1
	v_mov_b32_e32 v16, 0
	s_branch .LBB0_427

.LBB0_990:
	s_and_b64 vcc, exec, s[4:5]
	s_cbranch_vccz .LBB0_1045
	s_mov_b64 s[0:1], -1
	s_and_b64 vcc, exec, s[12:13]
	s_cbranch_vccz .LBB0_1020
	s_sub_i32 s3, s2, 32
	s_lshl_b32 s0, s3, 3
	s_add_i32 s8, s57, s0
	s_waitcnt vmcnt(0)
	v_readlane_b32 s60, v240, 1
	v_readlane_b32 s61, v240, 2
	v_readlane_b32 s62, v240, 3
	v_readlane_b32 s63, v240, 4
	v_readlane_b32 s64, v240, 5
	v_readlane_b32 s65, v240, 6
	v_readlane_b32 s66, v240, 7
	v_readlane_b32 s67, v240, 8
	s_add_i32 s9, s80, 0xffffff00
	s_mul_i32 s4, s57, 0x2100
	v_lshrrev_b32_e32 v55, 3, v146
	v_and_b32_e32 v56, 7, v146
	v_mul_u32_u24_e32 v44, 0x84, v55
	v_lshl_add_u32 v44, v56, 4, v44
	v_add_u32_e32 v44, s4, v44
	v_add_u32_e32 v45, 0x420, v44
	v_add_u32_e32 v46, 0x840, v44
	v_add_u32_e32 v47, 0xc60, v44
	v_add_u32_e32 v48, 0x1080, v44
	v_add_u32_e32 v49, 0x14a0, v44
	v_add_u32_e32 v50, 0x18c0, v44
	v_add_u32_e32 v51, 0x1ce0, v44
	v_mul_u32_u24_e32 v52, 0x420, v56
	v_lshl_add_u32 v52, v55, 2, v52
	v_add_u32_e32 v52, s4, v52
	v_lshrrev_b32_e32 v55, 3, v146
	v_and_b32_e32 v56, 7, v146
	s_mov_b32 s4, 0x5800
	v_mul_lo_u32 v53, v55, s4
	v_lshl_add_u32 v53, v56, 4, v53
	s_mov_b32 s4, 0x1000
	v_mul_lo_u32 v54, v55, s4
	v_lshl_add_u32 v54, v56, 4, v54
	s_mov_b32 s0, s8
	s_cmp_ge_u32 s0, 0x2c00
	s_cbranch_scc1 .Lcv_done_p7up
	s_lshr_b32 s10, s0, 5
	s_mul_i32 s10, s10, 0x1746
	s_lshr_b32 s10, s10, 16
	s_mul_i32 s11, s10, 352
	s_sub_u32 s11, s0, s11
	s_lshl_b32 s5, s11, 5
	s_lshr_b32 s6, s5, 8
	s_lshl_b32 s6, s6, 7
	s_and_b32 s7, s5, 0x7f
	s_add_u32 s6, s6, s7
	s_bitcmp1_b32 s5, 7
	s_mov_b32 s5, s6
	s_cselect_b32 s12, s64, s62
	s_cselect_b32 s13, s65, s63
	s_mul_i32 s6, s10, 0x160000
	s_lshl_b32 s5, s5, 2
	s_add_u32 s6, s6, s5
	s_add_u32 s12, s12, s6
	s_addc_u32 s13, s13, 0
	global_load_dwordx4 v[64:67], v53, s[12:13] nt
	s_add_u32 s12, s12, 0x2c000
	s_addc_u32 s13, s13, 0
	global_load_dwordx4 v[68:71], v53, s[12:13] nt
	s_add_u32 s12, s12, 0x2c000
	s_addc_u32 s13, s13, 0
	global_load_dwordx4 v[72:75], v53, s[12:13] nt
	s_add_u32 s12, s12, 0x2c000
	s_addc_u32 s13, s13, 0
	global_load_dwordx4 v[76:79], v53, s[12:13] nt
	s_add_u32 s12, s12, 0x2c000
	s_addc_u32 s13, s13, 0
	global_load_dwordx4 v[80:83], v53, s[12:13] nt
	s_add_u32 s12, s12, 0x2c000
	s_addc_u32 s13, s13, 0
	global_load_dwordx4 v[84:87], v53, s[12:13] nt
	s_add_u32 s12, s12, 0x2c000
	s_addc_u32 s13, s13, 0
	global_load_dwordx4 v[88:91], v53, s[12:13] nt
	s_add_u32 s12, s12, 0x2c000
	s_addc_u32 s13, s13, 0
	global_load_dwordx4 v[92:95], v53, s[12:13] nt
	s_add_u32 s1, s0, s9
	s_cmp_ge_u32 s1, 0x2c00
	s_cbranch_scc1 .Lcv_only1_p7up
	s_lshr_b32 s10, s1, 5
	s_mul_i32 s10, s10, 0x1746
	s_lshr_b32 s10, s10, 16
	s_mul_i32 s11, s10, 352
	s_sub_u32 s11, s1, s11
	s_lshl_b32 s5, s11, 5
	s_lshr_b32 s6, s5, 8
	s_lshl_b32 s6, s6, 7
	s_and_b32 s7, s5, 0x7f
	s_add_u32 s6, s6, s7
	s_bitcmp1_b32 s5, 7
	s_mov_b32 s5, s6
	s_cselect_b32 s12, s64, s62
	s_cselect_b32 s13, s65, s63
	s_mul_i32 s6, s10, 0x160000
	s_lshl_b32 s5, s5, 2
	s_add_u32 s6, s6, s5
	s_add_u32 s12, s12, s6
	s_addc_u32 s13, s13, 0
	global_load_dwordx4 v[96:99], v53, s[12:13] nt
	s_add_u32 s12, s12, 0x2c000
	s_addc_u32 s13, s13, 0
	global_load_dwordx4 v[100:103], v53, s[12:13] nt
	s_add_u32 s12, s12, 0x2c000
	s_addc_u32 s13, s13, 0
	global_load_dwordx4 v[104:107], v53, s[12:13] nt
	s_add_u32 s12, s12, 0x2c000
	s_addc_u32 s13, s13, 0
	global_load_dwordx4 v[108:111], v53, s[12:13] nt
	s_add_u32 s12, s12, 0x2c000
	s_addc_u32 s13, s13, 0
	global_load_dwordx4 v[112:115], v53, s[12:13] nt
	s_add_u32 s12, s12, 0x2c000
	s_addc_u32 s13, s13, 0
	global_load_dwordx4 v[116:119], v53, s[12:13] nt
	s_add_u32 s12, s12, 0x2c000
	s_addc_u32 s13, s13, 0
	global_load_dwordx4 v[120:123], v53, s[12:13] nt
	s_add_u32 s12, s12, 0x2c000
	s_addc_u32 s13, s13, 0
	global_load_dwordx4 v[124:127], v53, s[12:13] nt
	s_waitcnt vmcnt(8)
	s_branch .Lcv_procA_p7up

.Lcv_procA_p7up:
	s_lshr_b32 s10, s0, 5
	s_mul_i32 s10, s10, 0x1746
	s_lshr_b32 s10, s10, 16
	s_mul_i32 s11, s10, 352
	s_sub_u32 s11, s0, s11
	ds_write2_b32 v44, v64, v65 offset1:1
	ds_write2_b32 v44, v66, v67 offset0:2 offset1:3
	ds_write2_b32 v45, v68, v69 offset1:1
	ds_write2_b32 v45, v70, v71 offset0:2 offset1:3
	ds_write2_b32 v46, v72, v73 offset1:1
	ds_write2_b32 v46, v74, v75 offset0:2 offset1:3
	ds_write2_b32 v47, v76, v77 offset1:1
	ds_write2_b32 v47, v78, v79 offset0:2 offset1:3
	ds_write2_b32 v48, v80, v81 offset1:1
	ds_write2_b32 v48, v82, v83 offset0:2 offset1:3
	ds_write2_b32 v49, v84, v85 offset1:1
	ds_write2_b32 v49, v86, v87 offset0:2 offset1:3
	ds_write2_b32 v50, v88, v89 offset1:1
	ds_write2_b32 v50, v90, v91 offset0:2 offset1:3
	ds_write2_b32 v51, v92, v93 offset1:1
	ds_write2_b32 v51, v94, v95 offset0:2 offset1:3
	s_mul_i32 s5, s11, 0x20000
	s_lshl_b32 s6, s10, 7
	s_add_u32 s5, s5, s6
	s_add_u32 s14, s50, s5
	s_addc_u32 s15, s51, 0
	s_waitcnt lgkmcnt(0)
	ds_read2_b32 v[8:9], v52 offset0:0 offset1:33
	ds_read2_b32 v[10:11], v52 offset0:66 offset1:99
	ds_read2_b32 v[12:13], v52 offset0:132 offset1:165
	ds_read2_b32 v[14:15], v52 offset0:198 offset1:231
	ds_read2_b32 v[16:17], v52 offset0:8 offset1:41
	ds_read2_b32 v[18:19], v52 offset0:74 offset1:107
	ds_read2_b32 v[20:21], v52 offset0:140 offset1:173
	ds_read2_b32 v[22:23], v52 offset0:206 offset1:239
	ds_read2_b32 v[24:25], v52 offset0:16 offset1:49
	ds_read2_b32 v[26:27], v52 offset0:82 offset1:115
	ds_read2_b32 v[28:29], v52 offset0:148 offset1:181
	ds_read2_b32 v[30:31], v52 offset0:214 offset1:247
	ds_read2_b32 v[32:33], v52 offset0:24 offset1:57
	ds_read2_b32 v[34:35], v52 offset0:90 offset1:123
	ds_read2_b32 v[36:37], v52 offset0:156 offset1:189
	ds_read2_b32 v[38:39], v52 offset0:222 offset1:255
	s_waitcnt lgkmcnt(12)
	v_cvt_pk_bf16_f32 v148, v8, v9
	v_cvt_pk_bf16_f32 v149, v10, v11
	v_cvt_pk_bf16_f32 v150, v12, v13
	v_cvt_pk_bf16_f32 v151, v14, v15
	global_store_dwordx4 v54, v[148:151], s[14:15] nt
	s_add_u32 s14, s14, 0x8000
	s_addc_u32 s15, s15, 0
	s_waitcnt lgkmcnt(8)
	v_cvt_pk_bf16_f32 v152, v16, v17
	v_cvt_pk_bf16_f32 v153, v18, v19
	v_cvt_pk_bf16_f32 v154, v20, v21
	v_cvt_pk_bf16_f32 v155, v22, v23
	global_store_dwordx4 v54, v[152:155], s[14:15] nt
	s_add_u32 s14, s14, 0x8000
	s_addc_u32 s15, s15, 0
	s_waitcnt lgkmcnt(4)
	v_cvt_pk_bf16_f32 v156, v24, v25
	v_cvt_pk_bf16_f32 v157, v26, v27
	v_cvt_pk_bf16_f32 v158, v28, v29
	v_cvt_pk_bf16_f32 v159, v30, v31
	global_store_dwordx4 v54, v[156:159], s[14:15] nt
	s_add_u32 s14, s14, 0x8000
	s_addc_u32 s15, s15, 0
	s_waitcnt lgkmcnt(0)
	v_cvt_pk_bf16_f32 v160, v32, v33
	v_cvt_pk_bf16_f32 v161, v34, v35
	v_cvt_pk_bf16_f32 v162, v36, v37
	v_cvt_pk_bf16_f32 v163, v38, v39
	global_store_dwordx4 v54, v[160:163], s[14:15] nt
	s_cmp_ge_u32 s1, 0x2c00
	s_cbranch_scc1 .Lcv_done_p7up
	s_add_u32 s0, s1, s9
	s_cmp_ge_u32 s0, 0x2c00
	s_cbranch_scc1 .Lcv_tailB_p7up
	s_lshr_b32 s10, s0, 5
	s_mul_i32 s10, s10, 0x1746
	s_lshr_b32 s10, s10, 16
	s_mul_i32 s11, s10, 352
	s_sub_u32 s11, s0, s11
	s_lshl_b32 s5, s11, 5
	s_lshr_b32 s6, s5, 8
	s_lshl_b32 s6, s6, 7
	s_and_b32 s7, s5, 0x7f
	s_add_u32 s6, s6, s7
	s_bitcmp1_b32 s5, 7
	s_mov_b32 s5, s6
	s_cselect_b32 s12, s64, s62
	s_cselect_b32 s13, s65, s63
	s_mul_i32 s6, s10, 0x160000
	s_lshl_b32 s5, s5, 2
	s_add_u32 s6, s6, s5
	s_add_u32 s12, s12, s6
	s_addc_u32 s13, s13, 0
	global_load_dwordx4 v[64:67], v53, s[12:13] nt
	s_add_u32 s12, s12, 0x2c000
	s_addc_u32 s13, s13, 0
	global_load_dwordx4 v[68:71], v53, s[12:13] nt
	s_add_u32 s12, s12, 0x2c000
	s_addc_u32 s13, s13, 0
	global_load_dwordx4 v[72:75], v53, s[12:13] nt
	s_add_u32 s12, s12, 0x2c000
	s_addc_u32 s13, s13, 0
	global_load_dwordx4 v[76:79], v53, s[12:13] nt
	s_add_u32 s12, s12, 0x2c000
	s_addc_u32 s13, s13, 0
	global_load_dwordx4 v[80:83], v53, s[12:13] nt
	s_add_u32 s12, s12, 0x2c000
	s_addc_u32 s13, s13, 0
	global_load_dwordx4 v[84:87], v53, s[12:13] nt
	s_add_u32 s12, s12, 0x2c000
	s_addc_u32 s13, s13, 0
	global_load_dwordx4 v[88:91], v53, s[12:13] nt
	s_add_u32 s12, s12, 0x2c000
	s_addc_u32 s13, s13, 0
	global_load_dwordx4 v[92:95], v53, s[12:13] nt
	s_waitcnt vmcnt(12)
	s_branch .Lcv_procB_p7up

.Lcv_procB_p7up:
	s_lshr_b32 s10, s1, 5
	s_mul_i32 s10, s10, 0x1746
	s_lshr_b32 s10, s10, 16
	s_mul_i32 s11, s10, 352
	s_sub_u32 s11, s1, s11
	ds_write2_b32 v44, v96, v97 offset1:1
	ds_write2_b32 v44, v98, v99 offset0:2 offset1:3
	ds_write2_b32 v45, v100, v101 offset1:1
	ds_write2_b32 v45, v102, v103 offset0:2 offset1:3
	ds_write2_b32 v46, v104, v105 offset1:1
	ds_write2_b32 v46, v106, v107 offset0:2 offset1:3
	ds_write2_b32 v47, v108, v109 offset1:1
	ds_write2_b32 v47, v110, v111 offset0:2 offset1:3
	ds_write2_b32 v48, v112, v113 offset1:1
	ds_write2_b32 v48, v114, v115 offset0:2 offset1:3
	ds_write2_b32 v49, v116, v117 offset1:1
	ds_write2_b32 v49, v118, v119 offset0:2 offset1:3
	ds_write2_b32 v50, v120, v121 offset1:1
	ds_write2_b32 v50, v122, v123 offset0:2 offset1:3
	ds_write2_b32 v51, v124, v125 offset1:1
	ds_write2_b32 v51, v126, v127 offset0:2 offset1:3
	s_mul_i32 s5, s11, 0x20000
	s_lshl_b32 s6, s10, 7
	s_add_u32 s5, s5, s6
	s_add_u32 s14, s50, s5
	s_addc_u32 s15, s51, 0
	s_waitcnt lgkmcnt(0)
	ds_read2_b32 v[8:9], v52 offset0:0 offset1:33
	ds_read2_b32 v[10:11], v52 offset0:66 offset1:99
	ds_read2_b32 v[12:13], v52 offset0:132 offset1:165
	ds_read2_b32 v[14:15], v52 offset0:198 offset1:231
	ds_read2_b32 v[16:17], v52 offset0:8 offset1:41
	ds_read2_b32 v[18:19], v52 offset0:74 offset1:107
	ds_read2_b32 v[20:21], v52 offset0:140 offset1:173
	ds_read2_b32 v[22:23], v52 offset0:206 offset1:239
	ds_read2_b32 v[24:25], v52 offset0:16 offset1:49
	ds_read2_b32 v[26:27], v52 offset0:82 offset1:115
	ds_read2_b32 v[28:29], v52 offset0:148 offset1:181
	ds_read2_b32 v[30:31], v52 offset0:214 offset1:247
	ds_read2_b32 v[32:33], v52 offset0:24 offset1:57
	ds_read2_b32 v[34:35], v52 offset0:90 offset1:123
	ds_read2_b32 v[36:37], v52 offset0:156 offset1:189
	ds_read2_b32 v[38:39], v52 offset0:222 offset1:255
	s_waitcnt lgkmcnt(12)
	v_cvt_pk_bf16_f32 v148, v8, v9
	v_cvt_pk_bf16_f32 v149, v10, v11
	v_cvt_pk_bf16_f32 v150, v12, v13
	v_cvt_pk_bf16_f32 v151, v14, v15
	global_store_dwordx4 v54, v[148:151], s[14:15] nt
	s_add_u32 s14, s14, 0x8000
	s_addc_u32 s15, s15, 0
	s_waitcnt lgkmcnt(8)
	v_cvt_pk_bf16_f32 v152, v16, v17
	v_cvt_pk_bf16_f32 v153, v18, v19
	v_cvt_pk_bf16_f32 v154, v20, v21
	v_cvt_pk_bf16_f32 v155, v22, v23
	global_store_dwordx4 v54, v[152:155], s[14:15] nt
	s_add_u32 s14, s14, 0x8000
	s_addc_u32 s15, s15, 0
	s_waitcnt lgkmcnt(4)
	v_cvt_pk_bf16_f32 v156, v24, v25
	v_cvt_pk_bf16_f32 v157, v26, v27
	v_cvt_pk_bf16_f32 v158, v28, v29
	v_cvt_pk_bf16_f32 v159, v30, v31
	global_store_dwordx4 v54, v[156:159], s[14:15] nt
	s_add_u32 s14, s14, 0x8000
	s_addc_u32 s15, s15, 0
	s_waitcnt lgkmcnt(0)
	v_cvt_pk_bf16_f32 v160, v32, v33
	v_cvt_pk_bf16_f32 v161, v34, v35
	v_cvt_pk_bf16_f32 v162, v36, v37
	v_cvt_pk_bf16_f32 v163, v38, v39
	global_store_dwordx4 v54, v[160:163], s[14:15] nt
	s_cmp_ge_u32 s0, 0x2c00
	s_cbranch_scc1 .Lcv_done_p7up
	s_add_u32 s1, s0, s9
	s_cmp_ge_u32 s1, 0x2c00
	s_cbranch_scc1 .Lcv_tailA_p7up
	s_lshr_b32 s10, s1, 5
	s_mul_i32 s10, s10, 0x1746
	s_lshr_b32 s10, s10, 16
	s_mul_i32 s11, s10, 352
	s_sub_u32 s11, s1, s11
	s_lshl_b32 s5, s11, 5
	s_lshr_b32 s6, s5, 8
	s_lshl_b32 s6, s6, 7
	s_and_b32 s7, s5, 0x7f
	s_add_u32 s6, s6, s7
	s_bitcmp1_b32 s5, 7
	s_mov_b32 s5, s6
	s_cselect_b32 s12, s64, s62
	s_cselect_b32 s13, s65, s63
	s_mul_i32 s6, s10, 0x160000
	s_lshl_b32 s5, s5, 2
	s_add_u32 s6, s6, s5
	s_add_u32 s12, s12, s6
	s_addc_u32 s13, s13, 0
	global_load_dwordx4 v[96:99], v53, s[12:13] nt
	s_add_u32 s12, s12, 0x2c000
	s_addc_u32 s13, s13, 0
	global_load_dwordx4 v[100:103], v53, s[12:13] nt
	s_add_u32 s12, s12, 0x2c000
	s_addc_u32 s13, s13, 0
	global_load_dwordx4 v[104:107], v53, s[12:13] nt
	s_add_u32 s12, s12, 0x2c000
	s_addc_u32 s13, s13, 0
	global_load_dwordx4 v[108:111], v53, s[12:13] nt
	s_add_u32 s12, s12, 0x2c000
	s_addc_u32 s13, s13, 0
	global_load_dwordx4 v[112:115], v53, s[12:13] nt
	s_add_u32 s12, s12, 0x2c000
	s_addc_u32 s13, s13, 0
	global_load_dwordx4 v[116:119], v53, s[12:13] nt
	s_add_u32 s12, s12, 0x2c000
	s_addc_u32 s13, s13, 0
	global_load_dwordx4 v[120:123], v53, s[12:13] nt
	s_add_u32 s12, s12, 0x2c000
	s_addc_u32 s13, s13, 0
	global_load_dwordx4 v[124:127], v53, s[12:13] nt
	s_waitcnt vmcnt(12)
	s_branch .Lcv_procA_p7up

.Lcv_done_p7up:
.LBB0_1003:
	s_cmpk_gt_i32 s2, 0x11f
	v_readfirstlane_b32 s0, v144
	s_barrier
	s_cbranch_scc1 .LBB0_1019
	v_lshrrev_b32_e32 v0, 5, v144
	v_lshrrev_b32_e32 v2, 1, v144
	v_and_b32_e32 v0, 4, v0
	v_bfe_u32 v1, v144, 2, 2
	s_waitcnt vmcnt(14)
	v_and_b32_e32 v11, 24, v2
	v_or3_b32 v0, v0, v1, v11
	v_lshlrev_b32_e32 v1, 4, v144
	v_add_u32_e32 v8, 0x2000, v1
	v_lshrrev_b32_e32 v2, 7, v8
	s_movk_i32 s4, 0xe0
	v_and_b32_e32 v4, 32, v144
	s_add_u32 s28, s52, 0x9000000
	v_and_or_b32 v3, v2, s4, v0
	v_bitop3_b32 v9, v1, v4, 48 bitop3:0x6c
	v_and_b32_e32 v10, 64, v144
	s_waitcnt vmcnt(13)
	v_bfe_u32 v12, v144, 2, 4
	s_movk_i32 s4, 0xf0
	s_addc_u32 s29, s53, 0
	v_or_b32_e32 v1, v9, v10
	v_and_or_b32 v2, v2, s4, v12
	s_add_u32 s35, s52, 0x6d00000
	s_waitcnt vmcnt(0)
	v_lshl_or_b32 v130, v2, 11, v1
	v_lshrrev_b32_e32 v2, 3, v144
	s_movk_i32 s4, 0x60
	s_addc_u32 s42, s53, 0
	v_and_or_b32 v0, v2, s4, v0
	s_movk_i32 s4, 0x70
	s_lshl_b32 s5, s2, 5
	v_lshl_or_b32 v134, v0, 11, v1
	v_and_or_b32 v0, v2, s4, v12
	s_lshr_b32 s4, s3, 3
	s_and_b32 s5, s5, 0xe0
	s_add_i32 s5, s5, s4
	s_lshr_b32 s4, s5, 3
	s_and_b32 s4, s4, 0x7fffff8
	s_bfe_u32 s6, s3, 0x30003
	s_lshr_b32 s10, s0, 6
	s_or_b32 s4, s4, s6
	s_bfe_u32 s8, s5, 0x30003
	s_mov_b32 s5, 0
	s_lshr_b32 s1, s0, 8
	s_lshl_b32 s43, s10, 10
	s_lshl_b64 s[6:7], s[4:5], 19
	s_lshl_b32 s9, s8, 19
	s_add_u32 s36, s35, s9
	s_addc_u32 s37, s42, 0
	s_add_i32 s46, s43, 0
	s_add_i32 m0, s46, 0x10000
	v_lshl_or_b32 v128, v3, 11, v1
	global_load_lds_dwordx4 v134, s[36:37]
	s_add_i32 m0, s46, 0x12000
	s_add_u32 s12, s36, 0x40000
	global_load_lds_dwordx4 v128, s[36:37]
	s_addc_u32 s13, s37, 0
	s_add_i32 m0, s46, 0x14000
	v_lshl_or_b32 v136, v0, 11, v1
	global_load_lds_dwordx4 v134, s[12:13]
	s_add_i32 m0, s46, 0x16000
	s_add_u32 s26, s28, s6
	s_addc_u32 s27, s29, s7
	s_add_i32 s47, s46, 0x2000
	global_load_lds_dwordx4 v128, s[12:13]
	s_mov_b32 m0, s46
	s_add_u32 s6, s26, 0x40000
	global_load_lds_dwordx4 v136, s[26:27]
	s_mov_b32 m0, s47
	s_addc_u32 s7, s27, 0
	s_add_i32 s48, s46, 0x4000
	global_load_lds_dwordx4 v130, s[26:27]
	s_mov_b32 m0, s48
	s_add_i32 s49, s46, 0x6000
	global_load_lds_dwordx4 v136, s[6:7]
	s_mov_b32 m0, s49
	v_mov_b32_e32 v135, 0
	global_load_lds_dwordx4 v130, s[6:7]
	v_mov_b32_e32 v129, v135
	v_mov_b32_e32 v137, v135
	v_mov_b32_e32 v131, v135
	s_cmp_eq_u32 s1, 1
	v_lshl_add_u64 v[6:7], s[36:37], 0, v[134:135]
	v_lshl_add_u64 v[4:5], s[36:37], 0, v[128:129]
	v_lshl_add_u64 v[0:1], s[26:27], 0, v[136:137]
	s_cselect_b64 s[6:7], -1, 0
	s_cmp_lg_u32 s1, 1
	v_lshl_add_u64 v[2:3], s[26:27], 0, v[130:131]
	s_cbranch_scc1 .LBB0_1006
	s_barrier

.LBB0_1345:
	s_abs_i32 s0, s30
	s_waitcnt vmcnt(15)
	v_cvt_f32_u32_e32 v0, s0
	s_sub_i32 s1, 0, s0
	v_rcp_iflag_f32_e32 v0, v0
	s_nop 0
	v_mul_f32_e32 v0, 0x4f7ffffe, v0
	v_cvt_u32_f32_e32 v0, v0
	s_nop 0
	v_readfirstlane_b32 s3, v0
	s_mul_i32 s1, s1, s3
	s_mul_hi_u32 s1, s3, s1
	s_add_i32 s3, s3, s1
	s_mul_hi_u32 s1, s3, 0x580
	s_mul_i32 s1, s1, s0
	s_sub_i32 s1, 0x580, s1
	s_sub_i32 s3, s1, s0
	s_cmp_ge_u32 s1, s0
	s_cselect_b32 s1, s3, s1
	s_sub_i32 s3, s1, s0
	s_cmp_ge_u32 s1, s0
	s_cselect_b32 s4, s3, s1
	s_cmp_lg_u32 s4, 0
	s_cselect_b64 s[0:1], -1, 0
	s_cmp_ge_i32 s2, s4
	s_cselect_b64 s[6:7], -1, 0
	s_sub_i32 s3, s2, s4
	s_lshl_b32 s3, s3, 3
	s_and_b64 s[6:7], s[0:1], s[6:7]
	s_add_i32 s3, s57, s3
	s_and_b64 s[8:9], s[6:7], exec
	s_cselect_b32 s3, s3, s34
	s_xor_b64 s[6:7], s[0:1], s[6:7]
	s_cmpk_gt_i32 s3, 0x15ff
	s_cselect_b64 s[8:9], -1, 0
	s_or_b64 s[6:7], s[6:7], s[8:9]
	s_and_b64 vcc, exec, s[6:7]
	s_cbranch_vccnz .LBB0_1356
	s_sub_i32 s4, s30, s4
	s_lshl_b32 s4, s4, 3
	s_and_b64 s[0:1], s[0:1], exec
	s_cselect_b32 s8, s4, s80
	v_readlane_b32 s12, v240, 1
	v_readlane_b32 s18, v240, 7
	v_readlane_b32 s19, v240, 8
	s_waitcnt vmcnt(0)
	s_add_u32 s22, s52, 0x3100000
	s_addc_u32 s23, s53, 0
	s_mul_i32 s4, s57, 0x2100
	v_lshrrev_b32_e32 v55, 3, v146
	v_and_b32_e32 v56, 7, v146
	v_mul_u32_u24_e32 v44, 0x84, v55
	v_lshl_add_u32 v44, v56, 4, v44
	v_add_u32_e32 v44, s4, v44
	v_add_u32_e32 v45, 0x420, v44
	v_add_u32_e32 v46, 0x840, v44
	v_add_u32_e32 v47, 0xc60, v44
	v_add_u32_e32 v48, 0x1080, v44
	v_add_u32_e32 v49, 0x14a0, v44
	v_add_u32_e32 v50, 0x18c0, v44
	v_add_u32_e32 v51, 0x1ce0, v44
	v_mul_u32_u24_e32 v52, 0x420, v56
	v_lshl_add_u32 v52, v55, 2, v52
	v_add_u32_e32 v52, s4, v52
	v_lshrrev_b32_e32 v55, 3, v146
	v_and_b32_e32 v56, 7, v146
	s_mov_b32 s4, 0x2000
	v_mul_lo_u32 v53, v55, s4
	v_lshl_add_u32 v53, v56, 4, v53
	s_mov_b32 s4, 0x2c00
	v_mul_lo_u32 v54, v55, s4
	v_lshl_add_u32 v54, v56, 4, v54
	s_mov_b32 s0, s3
	s_cmp_ge_u32 s0, 0x1600
	s_cbranch_scc1 .Lcv_done_p12dn
	s_lshr_b32 s10, s0, 6
	s_and_b32 s11, s0, 63
	s_lshl_b32 s5, s11, 5
	s_mul_i32 s6, s10, 0x80000
	s_lshl_b32 s5, s5, 2
	s_add_u32 s6, s6, s5
	s_add_u32 s12, s18, s6
	s_addc_u32 s13, s19, 0
	global_load_dwordx4 v[64:67], v53, s[12:13] nt
	s_add_u32 s12, s12, 0x10000
	s_addc_u32 s13, s13, 0
	global_load_dwordx4 v[68:71], v53, s[12:13] nt
	s_add_u32 s12, s12, 0x10000
	s_addc_u32 s13, s13, 0
	global_load_dwordx4 v[72:75], v53, s[12:13] nt
	s_add_u32 s12, s12, 0x10000
	s_addc_u32 s13, s13, 0
	global_load_dwordx4 v[76:79], v53, s[12:13] nt
	s_add_u32 s12, s12, 0x10000
	s_addc_u32 s13, s13, 0
	global_load_dwordx4 v[80:83], v53, s[12:13] nt
	s_add_u32 s12, s12, 0x10000
	s_addc_u32 s13, s13, 0
	global_load_dwordx4 v[84:87], v53, s[12:13] nt
	s_add_u32 s12, s12, 0x10000
	s_addc_u32 s13, s13, 0
	global_load_dwordx4 v[88:91], v53, s[12:13] nt
	s_add_u32 s12, s12, 0x10000
	s_addc_u32 s13, s13, 0
	global_load_dwordx4 v[92:95], v53, s[12:13] nt
	s_add_u32 s1, s0, s8
	s_cmp_ge_u32 s1, 0x1600
	s_cbranch_scc1 .Lcv_only1_p12dn
	s_lshr_b32 s10, s1, 6
	s_and_b32 s11, s1, 63
	s_lshl_b32 s5, s11, 5
	s_mul_i32 s6, s10, 0x80000
	s_lshl_b32 s5, s5, 2
	s_add_u32 s6, s6, s5
	s_add_u32 s12, s18, s6
	s_addc_u32 s13, s19, 0
	global_load_dwordx4 v[96:99], v53, s[12:13] nt
	s_add_u32 s12, s12, 0x10000
	s_addc_u32 s13, s13, 0
	global_load_dwordx4 v[100:103], v53, s[12:13] nt
	s_add_u32 s12, s12, 0x10000
	s_addc_u32 s13, s13, 0
	global_load_dwordx4 v[104:107], v53, s[12:13] nt
	s_add_u32 s12, s12, 0x10000
	s_addc_u32 s13, s13, 0
	global_load_dwordx4 v[108:111], v53, s[12:13] nt
	s_add_u32 s12, s12, 0x10000
	s_addc_u32 s13, s13, 0
	global_load_dwordx4 v[112:115], v53, s[12:13] nt
	s_add_u32 s12, s12, 0x10000
	s_addc_u32 s13, s13, 0
	global_load_dwordx4 v[116:119], v53, s[12:13] nt
	s_add_u32 s12, s12, 0x10000
	s_addc_u32 s13, s13, 0
	global_load_dwordx4 v[120:123], v53, s[12:13] nt
	s_add_u32 s12, s12, 0x10000
	s_addc_u32 s13, s13, 0
	global_load_dwordx4 v[124:127], v53, s[12:13] nt
	s_waitcnt vmcnt(8)
	s_branch .Lcv_procA_p12dn

.Lcv_procA_p12dn:
	s_lshr_b32 s10, s0, 6
	s_and_b32 s11, s0, 63
	ds_write2_b32 v44, v64, v65 offset1:1
	ds_write2_b32 v44, v66, v67 offset0:2 offset1:3
	ds_write2_b32 v45, v68, v69 offset1:1
	ds_write2_b32 v45, v70, v71 offset0:2 offset1:3
	ds_write2_b32 v46, v72, v73 offset1:1
	ds_write2_b32 v46, v74, v75 offset0:2 offset1:3
	ds_write2_b32 v47, v76, v77 offset1:1
	ds_write2_b32 v47, v78, v79 offset0:2 offset1:3
	ds_write2_b32 v48, v80, v81 offset1:1
	ds_write2_b32 v48, v82, v83 offset0:2 offset1:3
	ds_write2_b32 v49, v84, v85 offset1:1
	ds_write2_b32 v49, v86, v87 offset0:2 offset1:3
	ds_write2_b32 v50, v88, v89 offset1:1
	ds_write2_b32 v50, v90, v91 offset0:2 offset1:3
	ds_write2_b32 v51, v92, v93 offset1:1
	ds_write2_b32 v51, v94, v95 offset0:2 offset1:3
	s_mul_i32 s5, s11, 0x58000
	s_lshl_b32 s6, s10, 7
	s_add_u32 s5, s5, s6
	s_add_u32 s14, s22, s5
	s_addc_u32 s15, s23, 0
	s_waitcnt lgkmcnt(0)
	ds_read2_b32 v[8:9], v52 offset0:0 offset1:33
	ds_read2_b32 v[10:11], v52 offset0:66 offset1:99
	ds_read2_b32 v[12:13], v52 offset0:132 offset1:165
	ds_read2_b32 v[14:15], v52 offset0:198 offset1:231
	ds_read2_b32 v[16:17], v52 offset0:8 offset1:41
	ds_read2_b32 v[18:19], v52 offset0:74 offset1:107
	ds_read2_b32 v[20:21], v52 offset0:140 offset1:173
	ds_read2_b32 v[22:23], v52 offset0:206 offset1:239
	ds_read2_b32 v[24:25], v52 offset0:16 offset1:49
	ds_read2_b32 v[26:27], v52 offset0:82 offset1:115
	ds_read2_b32 v[28:29], v52 offset0:148 offset1:181
	ds_read2_b32 v[30:31], v52 offset0:214 offset1:247
	ds_read2_b32 v[32:33], v52 offset0:24 offset1:57
	ds_read2_b32 v[34:35], v52 offset0:90 offset1:123
	ds_read2_b32 v[36:37], v52 offset0:156 offset1:189
	ds_read2_b32 v[38:39], v52 offset0:222 offset1:255
	s_waitcnt lgkmcnt(12)
	v_cvt_pk_bf16_f32 v128, v8, v9
	v_cvt_pk_bf16_f32 v129, v10, v11
	v_cvt_pk_bf16_f32 v130, v12, v13
	v_cvt_pk_bf16_f32 v131, v14, v15
	global_store_dwordx4 v54, v[128:131], s[14:15] nt
	s_add_u32 s14, s14, 0x16000
	s_addc_u32 s15, s15, 0
	s_waitcnt lgkmcnt(8)
	v_cvt_pk_bf16_f32 v132, v16, v17
	v_cvt_pk_bf16_f32 v133, v18, v19
	v_cvt_pk_bf16_f32 v134, v20, v21
	v_cvt_pk_bf16_f32 v135, v22, v23
	global_store_dwordx4 v54, v[132:135], s[14:15] nt
	s_add_u32 s14, s14, 0x16000
	s_addc_u32 s15, s15, 0
	s_waitcnt lgkmcnt(4)
	v_cvt_pk_bf16_f32 v136, v24, v25
	v_cvt_pk_bf16_f32 v137, v26, v27
	v_cvt_pk_bf16_f32 v138, v28, v29
	v_cvt_pk_bf16_f32 v139, v30, v31
	global_store_dwordx4 v54, v[136:139], s[14:15] nt
	s_add_u32 s14, s14, 0x16000
	s_addc_u32 s15, s15, 0
	s_waitcnt lgkmcnt(0)
	v_cvt_pk_bf16_f32 v140, v32, v33
	v_cvt_pk_bf16_f32 v141, v34, v35
	v_cvt_pk_bf16_f32 v142, v36, v37
	v_cvt_pk_bf16_f32 v143, v38, v39
	global_store_dwordx4 v54, v[140:143], s[14:15] nt
	s_cmp_ge_u32 s1, 0x1600
	s_cbranch_scc1 .Lcv_done_p12dn
	s_add_u32 s0, s1, s8
	s_cmp_ge_u32 s0, 0x1600
	s_cbranch_scc1 .Lcv_tailB_p12dn
	s_lshr_b32 s10, s0, 6
	s_and_b32 s11, s0, 63
	s_lshl_b32 s5, s11, 5
	s_mul_i32 s6, s10, 0x80000
	s_lshl_b32 s5, s5, 2
	s_add_u32 s6, s6, s5
	s_add_u32 s12, s18, s6
	s_addc_u32 s13, s19, 0
	global_load_dwordx4 v[64:67], v53, s[12:13] nt
	s_add_u32 s12, s12, 0x10000
	s_addc_u32 s13, s13, 0
	global_load_dwordx4 v[68:71], v53, s[12:13] nt
	s_add_u32 s12, s12, 0x10000
	s_addc_u32 s13, s13, 0
	global_load_dwordx4 v[72:75], v53, s[12:13] nt
	s_add_u32 s12, s12, 0x10000
	s_addc_u32 s13, s13, 0
	global_load_dwordx4 v[76:79], v53, s[12:13] nt
	s_add_u32 s12, s12, 0x10000
	s_addc_u32 s13, s13, 0
	global_load_dwordx4 v[80:83], v53, s[12:13] nt
	s_add_u32 s12, s12, 0x10000
	s_addc_u32 s13, s13, 0
	global_load_dwordx4 v[84:87], v53, s[12:13] nt
	s_add_u32 s12, s12, 0x10000
	s_addc_u32 s13, s13, 0
	global_load_dwordx4 v[88:91], v53, s[12:13] nt
	s_add_u32 s12, s12, 0x10000
	s_addc_u32 s13, s13, 0
	global_load_dwordx4 v[92:95], v53, s[12:13] nt
	s_waitcnt vmcnt(12)
	s_branch .Lcv_procB_p12dn

.Lcv_procB_p12dn:
	s_lshr_b32 s10, s1, 6
	s_and_b32 s11, s1, 63
	ds_write2_b32 v44, v96, v97 offset1:1
	ds_write2_b32 v44, v98, v99 offset0:2 offset1:3
	ds_write2_b32 v45, v100, v101 offset1:1
	ds_write2_b32 v45, v102, v103 offset0:2 offset1:3
	ds_write2_b32 v46, v104, v105 offset1:1
	ds_write2_b32 v46, v106, v107 offset0:2 offset1:3
	ds_write2_b32 v47, v108, v109 offset1:1
	ds_write2_b32 v47, v110, v111 offset0:2 offset1:3
	ds_write2_b32 v48, v112, v113 offset1:1
	ds_write2_b32 v48, v114, v115 offset0:2 offset1:3
	ds_write2_b32 v49, v116, v117 offset1:1
	ds_write2_b32 v49, v118, v119 offset0:2 offset1:3
	ds_write2_b32 v50, v120, v121 offset1:1
	ds_write2_b32 v50, v122, v123 offset0:2 offset1:3
	ds_write2_b32 v51, v124, v125 offset1:1
	ds_write2_b32 v51, v126, v127 offset0:2 offset1:3
	s_mul_i32 s5, s11, 0x58000
	s_lshl_b32 s6, s10, 7
	s_add_u32 s5, s5, s6
	s_add_u32 s14, s22, s5
	s_addc_u32 s15, s23, 0
	s_waitcnt lgkmcnt(0)
	ds_read2_b32 v[8:9], v52 offset0:0 offset1:33
	ds_read2_b32 v[10:11], v52 offset0:66 offset1:99
	ds_read2_b32 v[12:13], v52 offset0:132 offset1:165
	ds_read2_b32 v[14:15], v52 offset0:198 offset1:231
	ds_read2_b32 v[16:17], v52 offset0:8 offset1:41
	ds_read2_b32 v[18:19], v52 offset0:74 offset1:107
	ds_read2_b32 v[20:21], v52 offset0:140 offset1:173
	ds_read2_b32 v[22:23], v52 offset0:206 offset1:239
	ds_read2_b32 v[24:25], v52 offset0:16 offset1:49
	ds_read2_b32 v[26:27], v52 offset0:82 offset1:115
	ds_read2_b32 v[28:29], v52 offset0:148 offset1:181
	ds_read2_b32 v[30:31], v52 offset0:214 offset1:247
	ds_read2_b32 v[32:33], v52 offset0:24 offset1:57
	ds_read2_b32 v[34:35], v52 offset0:90 offset1:123
	ds_read2_b32 v[36:37], v52 offset0:156 offset1:189
	ds_read2_b32 v[38:39], v52 offset0:222 offset1:255
	s_waitcnt lgkmcnt(12)
	v_cvt_pk_bf16_f32 v128, v8, v9
	v_cvt_pk_bf16_f32 v129, v10, v11
	v_cvt_pk_bf16_f32 v130, v12, v13
	v_cvt_pk_bf16_f32 v131, v14, v15
	global_store_dwordx4 v54, v[128:131], s[14:15] nt
	s_add_u32 s14, s14, 0x16000
	s_addc_u32 s15, s15, 0
	s_waitcnt lgkmcnt(8)
	v_cvt_pk_bf16_f32 v132, v16, v17
	v_cvt_pk_bf16_f32 v133, v18, v19
	v_cvt_pk_bf16_f32 v134, v20, v21
	v_cvt_pk_bf16_f32 v135, v22, v23
	global_store_dwordx4 v54, v[132:135], s[14:15] nt
	s_add_u32 s14, s14, 0x16000
	s_addc_u32 s15, s15, 0
	s_waitcnt lgkmcnt(4)
	v_cvt_pk_bf16_f32 v136, v24, v25
	v_cvt_pk_bf16_f32 v137, v26, v27
	v_cvt_pk_bf16_f32 v138, v28, v29
	v_cvt_pk_bf16_f32 v139, v30, v31
	global_store_dwordx4 v54, v[136:139], s[14:15] nt
	s_add_u32 s14, s14, 0x16000
	s_addc_u32 s15, s15, 0
	s_waitcnt lgkmcnt(0)
	v_cvt_pk_bf16_f32 v140, v32, v33
	v_cvt_pk_bf16_f32 v141, v34, v35
	v_cvt_pk_bf16_f32 v142, v36, v37
	v_cvt_pk_bf16_f32 v143, v38, v39
	global_store_dwordx4 v54, v[140:143], s[14:15] nt
	s_cmp_ge_u32 s0, 0x1600
	s_cbranch_scc1 .Lcv_done_p12dn
	s_add_u32 s1, s0, s8
	s_cmp_ge_u32 s1, 0x1600
	s_cbranch_scc1 .Lcv_tailA_p12dn
	s_lshr_b32 s10, s1, 6
	s_and_b32 s11, s1, 63
	s_lshl_b32 s5, s11, 5
	s_mul_i32 s6, s10, 0x80000
	s_lshl_b32 s5, s5, 2
	s_add_u32 s6, s6, s5
	s_add_u32 s12, s18, s6
	s_addc_u32 s13, s19, 0
	global_load_dwordx4 v[96:99], v53, s[12:13] nt
	s_add_u32 s12, s12, 0x10000
	s_addc_u32 s13, s13, 0
	global_load_dwordx4 v[100:103], v53, s[12:13] nt
	s_add_u32 s12, s12, 0x10000
	s_addc_u32 s13, s13, 0
	global_load_dwordx4 v[104:107], v53, s[12:13] nt
	s_add_u32 s12, s12, 0x10000
	s_addc_u32 s13, s13, 0
	global_load_dwordx4 v[108:111], v53, s[12:13] nt
	s_add_u32 s12, s12, 0x10000
	s_addc_u32 s13, s13, 0
	global_load_dwordx4 v[112:115], v53, s[12:13] nt
	s_add_u32 s12, s12, 0x10000
	s_addc_u32 s13, s13, 0
	global_load_dwordx4 v[116:119], v53, s[12:13] nt
	s_add_u32 s12, s12, 0x10000
	s_addc_u32 s13, s13, 0
	global_load_dwordx4 v[120:123], v53, s[12:13] nt
	s_add_u32 s12, s12, 0x10000
	s_addc_u32 s13, s13, 0
	global_load_dwordx4 v[124:127], v53, s[12:13] nt
	s_waitcnt vmcnt(12)
	s_branch .Lcv_procA_p12dn

.Lcv_done_p12dn:
.LBB0_1356:
	s_waitcnt vmcnt(0)
	s_barrier
	s_mov_b64 s[0:1], exec
	v_readlane_b32 s4, v240, 9
	v_readlane_b32 s5, v240, 10
	s_and_b64 s[4:5], s[0:1], s[4:5]
	s_mov_b64 exec, s[4:5]
	s_cbranch_execz .LBB0_1408
	s_add_i32 s3, 0, 0x23fc0
	s_waitcnt vmcnt(15)
	v_mov_b32_e32 v0, s3
	s_waitcnt vmcnt(0) expcnt(0) lgkmcnt(0)
	ds_read_b32 v2, v0
	s_add_i32 s3, 0, 0x23fc4
	v_mov_b32_e32 v0, s3
	ds_read_b32 v0, v0
	s_waitcnt lgkmcnt(1)
	v_cmp_ne_u32_e32 vcc, 0, v2
	s_cbranch_vccnz .LBB0_1372
	s_add_u32 s4, s52, 0x40200
	s_addc_u32 s5, s53, 0
	s_add_u32 s6, s52, 0x40400
	s_addc_u32 s7, s53, 0
	s_add_u32 s8, s52, 0x40500
	s_addc_u32 s9, s53, 0
	s_add_u32 s12, s52, 0x40600
	s_addc_u32 s13, s53, 0
	s_add_u32 s14, s52, 0x40700
	s_addc_u32 s15, s53, 0
	s_add_u32 s16, s52, 0x40800
	s_addc_u32 s17, s53, 0
	s_add_u32 s18, s52, 0x40900
	s_addc_u32 s19, s53, 0
	s_add_u32 s20, s52, 0x40a00
	s_addc_u32 s21, s53, 0
	s_add_u32 s22, s52, 0x40b00
	s_addc_u32 s23, s53, 0
	s_add_u32 s26, s52, 0x40c00
	s_addc_u32 s27, s53, 0
	s_add_u32 s36, s52, 0x40d00
	s_addc_u32 s37, s53, 0
	s_add_u32 s38, s52, 0x40e00
	s_addc_u32 s39, s53, 0
	s_add_u32 s40, s52, 0x40f00
	s_addc_u32 s41, s53, 0
	s_add_u32 s42, s52, 0x41000
	s_addc_u32 s43, s53, 0
	s_add_u32 s46, s52, 0x41100
	s_addc_u32 s47, s53, 0
	s_add_u32 s10, s52, 0x41200
	v_readlane_b32 s3, v240, 0
	s_addc_u32 s11, s53, 0
	s_mul_i32 s3, s31, s3
	s_add_u32 s28, s52, 0x41300
	s_mul_i32 s3, s3, s30
	s_addc_u32 s29, s53, 0
	s_mov_b32 s33, 1
	v_mov_b32_e32 v16, 0
	s_branch .LBB0_1360
